# attention key loop: waves 4-7 run PV after the iteration barrier (half-iteration stagger, V tiles triple-buffered) on top of the idle-window weight transposition
# baseline (speedup 1.0000x reference)
; #define LAS __attribute__((address_space(3)))
; __device__ __forceinline__ unsigned xb_ld(unsigned* p)              { return __hip_atomic_load(p, __ATOMIC_RELAXED, __HIP_MEMORY_SCOPE_AGENT); }
; __device__ __forceinline__ unsigned xb_add(unsigned* p, unsigned v) { return __hip_atomic_fetch_add(p, v, __ATOMIC_RELAXED, __HIP_MEMORY_SCOPE_AGENT); }
; __device__ __forceinline__ unsigned xb_xcc_id() { return (unsigned)__builtin_amdgcn_s_getreg((3 << 11) | 20) & 0xFu; }
; __device__ __forceinline__ XcdBarrier xcd_barrier_post(unsigned* bar, volatile LAS unsigned* st) {
;     XcdBarrier b; b.bar = bar; b.x = xb_xcc_id(); b.st = st;
;     if (threadIdx.x == 0) (void)xb_add(&bar[XB_XCNT(b.x)], 1u);
;     return b;
; }
; __device__ __forceinline__ void xcd_barrier_complete(unsigned* bar, unsigned x, unsigned& nloc, unsigned& nx) {
;     const unsigned G = gridDim.x * gridDim.y * gridDim.z;
;     unsigned sum, cnt, mine, sp = 0u;
;     for (;;) {
;         sum = 0u; cnt = 0u; mine = 0u;
; #pragma unroll
;         for (unsigned j = 0; j < 16; ++j) { const unsigned c = xb_ld(&bar[XB_XCNT(j)]); sum += c; cnt += (c > 0u) ? 1u : 0u; mine = (j == x) ? c : mine; }
;         if (sum == G) break;
;         __builtin_amdgcn_s_sleep(1);
;         if ((++sp & 255u) == 0u) { if (xb_ld(&bar[XB_TMO])) break; if (sp > XB_SPIN_CAP) { atomicAdd(&bar[XB_TMO], 1u); break; } }
;     }
;     nloc = mine > 0u ? mine : 1u; nx = cnt > 0u ? cnt : 1u;
; }
; __global__ void __launch_bounds__(512, 2) mega_fwd(Params P) {
;     extern __shared__ __attribute__((aligned(16))) unsigned char lds_raw[];
;     LAS unsigned char* lds = (LAS unsigned char*)lds_raw;
;     cg::grid_group grid = cg::this_grid();
;     const int G = gridDim.x, c = blockIdx.x;
;     volatile LAS unsigned* bst = (volatile LAS unsigned*)(lds + 131072 + 512);
;     if (threadIdx.x < 2) bst[threadIdx.x] = 0u;
;     if (c == 0) for (int i = threadIdx.x; i < XCD_BAR_WORDS; i += 512) __hip_atomic_store((unsigned*)(P.ws + WS_BAR) + i, 0u, __ATOMIC_RELAXED, __HIP_MEMORY_SCOPE_AGENT);
;     grid.sync();
;     const XcdBarrier xbar = xcd_barrier_post((unsigned*)(P.ws + WS_BAR), bst);
.LBB0_20:
	s_or_b64 exec, exec, s[6:7]
	s_lshl_b32 s51, s2, 3
	s_lshl_b32 s52, s64, 3
	s_lshl_b32 s6, s2, 9
	s_lshl_b32 s70, s64, 9
	s_cmpk_lt_i32 s2, 0x100
	v_writelane_b32 v252, s6, 4
	s_cselect_b64 s[6:7], -1, 0
	s_add_u32 s94, s0, 0x2b910200
	s_addc_u32 s95, s1, 0
	s_add_u32 s96, s0, 0x2b910400
	s_addc_u32 s97, s1, 0
	s_add_u32 s90, s0, 0x2b910500
	s_addc_u32 s91, s1, 0
	s_add_u32 s88, s0, 0x2b910600
	s_addc_u32 s89, s1, 0
	s_add_u32 s92, s0, 0x2b910700
	s_addc_u32 s93, s1, 0
	s_add_u32 s74, s0, 0x2b910800
	v_writelane_b32 v252, s6, 5
	s_addc_u32 s75, s1, 0
	s_mul_i32 s65, s65, s64
	v_writelane_b32 v252, s7, 6
	s_add_u32 s6, s0, 0x2b910900
	s_addc_u32 s7, s1, 0
	v_writelane_b32 v252, s6, 7
	v_mov_b32_e32 v209, 0x358637bd
	v_mov_b32_e32 v210, 0x3c0881c4
	v_writelane_b32 v252, s7, 8
	s_add_u32 s6, s0, 0x2b910a00
	s_addc_u32 s7, s1, 0
	v_writelane_b32 v252, s6, 9
	v_mov_b32_e32 v211, 0xbab64f3b
	v_mov_b32_e32 v213, 0x260
	v_writelane_b32 v252, s7, 10
	s_add_u32 s6, s0, 0x2b910b00
	s_addc_u32 s7, s1, 0
	v_writelane_b32 v252, s6, 11
	v_mov_b32_e32 v215, 0xc000
	v_mov_b32_e32 v216, 0x7f800000
	v_writelane_b32 v252, s7, 12
	s_add_u32 s6, s0, 0x2b910c00
	s_addc_u32 s7, s1, 0
	v_writelane_b32 v252, s6, 13
	v_mov_b32_e32 v164, 0x3f317218
	v_not_b32_e32 v217, 63
	v_writelane_b32 v252, s7, 14
	s_add_u32 s6, s0, 0x2b910d00
	s_addc_u32 s7, s1, 0
	v_writelane_b32 v252, s6, 15
	v_not_b32_e32 v218, 31
	v_mov_b32_e32 v219, 0x7fc00000
	v_writelane_b32 v252, s7, 16
	s_add_u32 s6, s0, 0x2b910e00
	s_addc_u32 s7, s1, 0
	v_writelane_b32 v252, s6, 17
	v_mov_b32_e32 v221, 0xff800000
	v_mov_b32_e32 v223, 0xb000
	v_writelane_b32 v252, s7, 18
	s_add_u32 s6, s0, 0x2b910f00
	s_addc_u32 s7, s1, 0
	v_writelane_b32 v252, s6, 19
	s_movk_i32 s72, 0x208
	s_mov_b32 s33, 0x7e07e07f
	v_writelane_b32 v252, s7, 20
	s_add_u32 s6, s0, 0x2b911000
	s_addc_u32 s7, s1, 0
	s_add_u32 s10, s0, 0x2b911100
	v_writelane_b32 v252, s6, 21
	s_addc_u32 s11, s1, 0
	s_movk_i32 s63, 0x1800
	v_writelane_b32 v252, s7, 22
	s_add_u32 s6, s0, 0x2b911200
	s_addc_u32 s7, s1, 0
	s_add_u32 s8, s0, 0x2b911300
	s_addc_u32 s9, s1, 0
	s_cmp_eq_u32 s3, 15
	s_cselect_b64 s[14:15], -1, 0
	v_writelane_b32 v252, s14, 23
	s_cmp_eq_u32 s3, 14
	s_movk_i32 s42, 0x40ff
	v_writelane_b32 v252, s15, 24
	s_cselect_b64 s[14:15], -1, 0
	v_writelane_b32 v252, s14, 25
	s_cmp_eq_u32 s3, 13
	s_movk_i32 s76, 0x5ff
	v_writelane_b32 v252, s15, 26
	s_cselect_b64 s[14:15], -1, 0
	v_writelane_b32 v252, s14, 27
	s_cmp_eq_u32 s3, 12
	s_movk_i32 s73, 0x2000
	v_writelane_b32 v252, s15, 28
	s_cselect_b64 s[14:15], -1, 0
	v_writelane_b32 v252, s14, 29
	s_cmp_eq_u32 s3, 11
	s_movk_i32 s50, 0x6000
	v_writelane_b32 v252, s15, 30
	s_cselect_b64 s[14:15], -1, 0
	v_writelane_b32 v252, s14, 31
	s_cmp_eq_u32 s3, 10
	s_mov_b32 s53, 0x8000
	v_writelane_b32 v252, s15, 32
	s_cselect_b64 s[14:15], -1, 0
	v_writelane_b32 v252, s14, 33
	s_cmp_eq_u32 s3, 9
	s_mov_b32 s54, 0xa000
	v_writelane_b32 v252, s15, 34
	s_cselect_b64 s[14:15], -1, 0
	v_writelane_b32 v252, s14, 35
	s_cmp_eq_u32 s3, 8
	s_mov_b32 s55, 0xc000
	v_writelane_b32 v252, s15, 36
	s_cselect_b64 s[14:15], -1, 0
	v_writelane_b32 v252, s14, 37
	s_cmp_eq_u32 s3, 7
	s_mov_b32 s56, 0xe000
	v_writelane_b32 v252, s15, 38
	s_cselect_b64 s[14:15], -1, 0
	v_writelane_b32 v252, s14, 39
	s_cmp_eq_u32 s3, 6
	s_mov_b32 s57, 0x16000
	v_writelane_b32 v252, s15, 40
	s_cselect_b64 s[14:15], -1, 0
	v_writelane_b32 v252, s14, 41
	s_cmp_eq_u32 s3, 5
	s_movk_i32 s77, 0x80
	v_writelane_b32 v252, s15, 42
	s_cselect_b64 s[14:15], -1, 0
	v_writelane_b32 v252, s14, 43
	s_cmp_eq_u32 s3, 4
	s_mov_b32 s78, 0x3fb8aa3b
	v_writelane_b32 v252, s15, 44
	s_cselect_b64 s[14:15], -1, 0
	v_writelane_b32 v252, s14, 45
	s_cmp_eq_u32 s3, 3
	s_mov_b32 s79, 0xc2ce8ed0
	v_writelane_b32 v252, s15, 46
	s_cselect_b64 s[14:15], -1, 0
	v_writelane_b32 v252, s14, 47
	s_cmp_eq_u32 s3, 2
	s_mov_b32 s80, 0x42b17218
	v_writelane_b32 v252, s15, 48
	s_cselect_b64 s[14:15], -1, 0
	v_writelane_b32 v252, s14, 49
	s_cmp_eq_u32 s3, 1
	s_brev_b32 s81, 18
	v_writelane_b32 v252, s15, 50
	s_cselect_b64 s[14:15], -1, 0
	v_writelane_b32 v252, s14, 51
	s_cmp_eq_u32 s3, 0
	s_brev_b32 s82, 1
	v_writelane_b32 v252, s15, 52
	s_cselect_b64 s[14:15], -1, 0
	s_lshl_b32 s3, s12, 2
	s_add_u32 s3, s4, s3
	s_addc_u32 s4, s5, 0
	v_writelane_b32 v252, s14, 53
	s_add_u32 s12, s3, 0x1400
	s_addc_u32 s13, s4, 0
	v_writelane_b32 v252, s15, 54
	v_writelane_b32 v252, s12, 55
	s_movk_i32 s83, 0x1f8
	s_movk_i32 s84, 0x2800
	v_writelane_b32 v252, s13, 56
	s_add_u32 s12, s3, 0x2400
	s_addc_u32 s13, s4, 0
	v_writelane_b32 v252, s12, 57
	s_add_u32 s4, s0, 0x2b913400
	s_addc_u32 s5, s1, 0
	v_writelane_b32 v252, s13, 58
	v_writelane_b32 v252, s4, 59
	s_add_u32 s0, s0, 0x2b913500
	s_addc_u32 s1, s1, 0
	v_writelane_b32 v252, s5, 60
	v_writelane_b32 v252, s0, 61
	s_cmpk_lt_i32 s2, 0xc30
	s_movk_i32 s85, 0x500
	v_writelane_b32 v252, s1, 62
	s_cselect_b64 s[0:1], -1, 0
	v_writelane_b32 v252, s0, 63
	s_ashr_i32 s3, s2, 31
	s_mov_b32 s86, 0xf800000
	v_writelane_b32 v253, s1, 0
	s_lshr_b32 s0, s3, 29
	s_add_i32 s1, s2, s0
	s_ashr_i32 s0, s1, 3
	s_and_b32 s1, s1, -8
	s_sub_i32 s4, s2, s1
	s_cmpk_lt_i32 s2, 0x820
	s_cselect_b64 s[12:13], -1, 0
	v_writelane_b32 v253, s12, 1
	s_cmpk_lt_i32 s2, 0x208
	s_mul_hi_i32 s1, s2, 0x7e07e07f
	v_writelane_b32 v253, s13, 2
	s_cselect_b64 s[12:13], -1, 0
	s_lshr_b32 s5, s1, 31
	s_ashr_i32 s1, s1, 5
	s_add_i32 s14, s1, s5
	s_mul_i32 s1, s14, 0xffffffbf
	v_writelane_b32 v253, s12, 3
	s_add_i32 s16, s1, s2
	s_ashr_i32 s17, s16, 31
	v_writelane_b32 v253, s13, 4
	s_mov_b32 s12, s16
	v_writelane_b32 v253, s12, 5
	s_ashr_i32 s15, s14, 31
	s_sub_u32 vcc_lo, 0xff, s2
;     __device__ __forceinline__ bool next(int i, Unit& u) const {
;         const int nfull = (nM - 1) * nN, rounds = nfull / G;
;         int pm, pn, br, pc = 0;
;         if (i < 3 * rounds) { const int r = i / 3; br = i - 3 * r; dense_tile(r * G + c, nM - 1, nN, pm, pn); u.nt = ntk; u.aux = br; }
;         else { const int s_ = (i - 3 * rounds) * G + c; if (s_ >= nN * 3 * pieces) return false;
;             pn = s_ / (3 * pieces); const int rem = s_ - pn * 3 * pieces; br = rem / pieces; pc = rem - br * pieces; pm = nM - 1; u.nt = ntk / pieces; u.aux = br | ((1 + pc) << 2); }
;         u.pm = pm; u.pn = pn;
;         const int acol = br == 0 ? C_AG : (br == 1 ? C_Q : C_K);
;         u.A = (const char*)(A0 + (size_t)pm * 256 * lda + acol + (size_t)pc * (ntk / pieces) * 64);
;         u.B = (const char*)(Bt + (size_t)br * 2048 * 1024 + (size_t)pn * 256 * ldb + (size_t)pc * (ntk / pieces) * 64); return true;
	s_mul_hi_i32 s1, vcc_lo, 0x55555556
	v_writelane_b32 v253, s13, 6
	s_lshl_b64 s[12:13], s[16:17], 19
	v_writelane_b32 v253, s12, 7
	s_mov_b32 s87, 0xff800000
	s_mov_b64 s[36:37], 0x10000
	v_writelane_b32 v253, s13, 8
	s_lshl_b64 s[12:13], s[14:15], 8
	v_writelane_b32 v253, s12, 9
	s_mov_b64 s[38:39], 0x28000
	s_mov_b32 s62, 0x3b808081
	v_writelane_b32 v253, s13, 10
	s_mov_b32 s12, s14
	v_writelane_b32 v253, s12, 11
	s_mov_b32 s28, s69
	s_nop 0
	v_writelane_b32 v253, s13, 12
	s_lshl_b64 s[12:13], s[14:15], 17
	v_writelane_b32 v253, s12, 13
	s_cmpk_lt_i32 vcc_lo, 0xc0
	s_nop 0
	v_writelane_b32 v253, s13, 14
	s_cselect_b64 s[12:13], -1, 0
	s_lshr_b32 s5, s1, 31
	s_add_i32 s14, s1, s5
	v_writelane_b32 v253, s12, 15
	s_mul_i32 s1, s14, -3
	s_add_i32 s1, s1, vcc_lo
	v_writelane_b32 v253, s13, 16
	v_writelane_b32 v253, s1, 17
	s_not_b32 s1, s2
	s_add_i32 s1, s64, s1
	v_writelane_b32 v253, s1, 18
	s_mov_b32 s12, s14
	s_ashr_i32 s15, s14, 31
	v_writelane_b32 v253, s12, 19
	s_mul_hi_i32 s1, s2, 0x2aaaaaab
	s_nop 0
	v_writelane_b32 v253, s13, 20
	s_lshl_b64 s[12:13], s[14:15], 17
	v_writelane_b32 v253, s12, 21
	s_cmpk_lt_i32 s2, 0x180
	s_nop 0
	v_writelane_b32 v253, s13, 22
	s_cselect_b64 s[12:13], -1, 0
	v_writelane_b32 v253, s12, 23
	s_lshr_b32 s5, s1, 31
	s_add_i32 s1, s1, s5
	v_writelane_b32 v253, s13, 24
	v_writelane_b32 v253, s1, 25
	s_mul_i32 s1, s1, -6
	s_add_i32 s1, s1, s2
	s_lshr_b32 s5, s1, 31
	s_add_i32 s5, s1, s5
	s_and_b32 s12, s5, -2
	s_sub_i32 s1, s1, s12
	v_writelane_b32 v253, s1, 26
	s_ashr_i32 s1, s5, 1
	s_cmpk_lt_i32 s2, 0x104
	v_writelane_b32 v253, s1, 27
	s_cselect_b64 s[12:13], -1, 0
	v_writelane_b32 v253, s12, 28
	s_lshl_b32 s1, s4, 5
	s_or_b32 s1, s1, 4
	v_writelane_b32 v253, s13, 29
	s_lshl_b32 s5, s4, 6
	s_lshl_b64 s[12:13], s[2:3], 17
	v_writelane_b32 v253, s12, 30
	s_cmpk_lt_i32 s2, 0x200
	s_nop 0
	v_writelane_b32 v253, s13, 31
	s_cselect_b64 s[12:13], -1, 0
	v_writelane_b32 v253, s12, 32
	s_cmpk_gt_i32 s2, 0x1ff
	s_nop 0
	v_writelane_b32 v253, s13, 33
	s_cselect_b64 s[12:13], -1, 0
	s_add_i32 s3, s2, 0xfffffe00
	v_writelane_b32 v253, s12, 34
	s_cmp_lt_u32 s3, 32
	s_nop 0
	v_writelane_b32 v253, s13, 35
	s_cselect_b64 s[12:13], -1, 0
	v_writelane_b32 v253, s12, 36
	s_nop 1
	v_writelane_b32 v253, s13, 37
	s_bfe_u32 s12, s2, 0x30002
	v_writelane_b32 v253, s12, 38
	s_lshl_b32 s12, s12, 2
	s_sub_i32 s12, s3, s12
	v_writelane_b32 v253, s12, 39
	s_cmpk_lt_i32 s2, 0xb2c
	s_mul_i32 s12, s4, 0x165
	s_cselect_b64 s[14:15], -1, 0
	s_add_i32 s12, s12, 4
	v_writelane_b32 v253, s14, 40
	s_cmpk_lt_u32 s3, 0x58
	s_nop 0
	v_writelane_b32 v253, s15, 41
	s_cselect_b64 s[14:15], -1, 0
	s_and_b32 s13, s2, 0xff
	s_mulk_i32 s13, 0x75
	v_writelane_b32 v253, s14, 42
	s_lshr_b32 s13, s13, 8
	s_nop 0
	v_writelane_b32 v253, s15, 43
	s_sub_i32 s14, s2, s13
	s_bfe_u32 s14, s14, 0x70001
	s_add_i32 s14, s14, s13
	s_bfe_u32 s13, s14, 0x50003
	v_writelane_b32 v253, s13, 44
	s_mul_i32 s13, s13, -11
	s_add_i32 s3, s13, s3
	v_writelane_b32 v253, s3, 45
	s_cmp_lt_i32 s4, 4
	s_mul_i32 s3, s4, 33
	s_cselect_b32 s3, s3, s1
	s_mul_i32 s1, s4, 0x166
	s_cselect_b32 s12, s1, s12
	s_abs_i32 s1, s64
	v_cvt_f32_u32_e32 v0, s1
	s_sub_i32 s13, 0, s1
	s_ashr_i32 s15, s64, 31
	v_rcp_iflag_f32_e32 v0, v0
	s_nop 0
	v_mul_f32_e32 v0, 0x4f7ffffe, v0
	v_cvt_u32_f32_e32 v0, v0
	s_nop 0
	v_readfirstlane_b32 s14, v0
	s_mul_i32 s13, s13, s14
	s_mul_hi_u32 s13, s14, s13
	s_add_i32 s14, s14, s13
	s_lshr_b32 s13, s14, 23
	s_mul_i32 s14, s13, s1
	s_sub_i32 s14, 0x200, s14
	s_add_i32 s16, s13, 1
	s_sub_i32 s17, s14, s1
	s_cmp_ge_u32 s14, s1
	s_cselect_b32 s13, s16, s13
	s_cselect_b32 s14, s17, s14
	s_add_i32 s16, s13, 1
	s_cmp_ge_u32 s14, s1
	s_cselect_b32 s1, s16, s13
	s_xor_b32 s1, s1, s15
	s_sub_i32 s1, s1, s15
	s_cmp_lt_i32 s4, 0
	s_movk_i32 s13, 0x187
	s_cselect_b32 s13, s13, 0x186
	s_mul_i32 s13, s4, s13
	s_mulk_i32 s4, 0x41
	s_cselect_b32 s4, s4, s5
	s_add_i32 s13, s13, s0
	s_mul_hi_i32 s5, s13, 0x2aaaaaab
	s_lshr_b32 s14, s5, 31
	s_ashr_i32 s5, s5, 6
	s_add_i32 s5, s5, s14
	s_mul_i32 s14, s5, 0x180
	s_add_i32 s3, s3, s0
	s_sub_i32 s13, s13, s14
	s_ashr_i32 s14, s3, 31
	s_lshr_b32 s14, s14, 27
	s_add_i32 s14, s3, s14
	s_and_b32 s15, s14, 0xffffffe0
	s_add_i32 s4, s4, s0
	s_sub_i32 s3, s3, s15
	s_ashr_i32 s15, s4, 31
	s_lshr_b32 s15, s15, 26
	s_add_i32 s15, s4, s15
	s_add_i32 s12, s12, s0
	s_and_b32 s16, s15, 0xffffffc0
	s_mul_hi_i32 s0, s12, 0x2e8ba2e9
	s_sub_i32 s16, s4, s16
	s_lshr_b32 s4, s0, 31
	s_ashr_i32 s0, s0, 6
	s_add_i32 s0, s0, s4
	s_mul_i32 s4, s0, 0x160
	s_sub_i32 s17, s12, s4
	s_lshl_b32 s12, s5, 3
	s_sub_i32 s4, 0x41, s12
	s_min_u32 s18, s4, 8
	s_ashr_i32 s4, s14, 5
	s_lshl_b32 s14, s4, 3
	s_sub_i32 s4, 0x41, s14
	s_min_u32 s19, s4, 8
	s_ashr_i32 s4, s15, 6
	s_lshl_b32 s15, s4, 3
	s_sub_i32 s4, 64, s15
	s_min_i32 s20, s4, 8
	s_bfe_i32 s4, s16, 0x80000
	v_cvt_f32_ubyte0_e32 v1, s18
	s_bfe_u32 s4, s4, 0x3000c
	v_cvt_f32_i32_e32 v0, s13
	v_rcp_iflag_f32_e32 v2, v1
	s_add_i32 s4, s16, s4
	s_bfe_i32 s5, s4, 0x80000
	s_and_b32 s4, s4, 0xf8
	s_sub_i32 s4, s16, s4
	s_sext_i32_i8 s4, s4
	v_mul_f32_e32 v2, v0, v2
	s_sext_i32_i16 s5, s5
	s_add_i32 s4, s15, s4
	v_trunc_f32_e32 v2, v2
	v_writelane_b32 v253, s4, 46
	s_ashr_i32 s4, s5, 3
	s_lshl_b32 s21, s0, 3
	v_fma_f32 v0, -v2, v1, v0
	v_writelane_b32 v253, s4, 47
	s_sub_i32 s0, 0x41, s21
	v_cmp_ge_f32_e64 s[4:5], |v0|, v1
	v_cvt_i32_f32_e32 v0, v2
	s_min_u32 s22, s0, 8
	s_ashr_i32 s0, s13, 30
	s_or_b32 s0, s0, 1
	s_and_b64 s[4:5], s[4:5], exec
	s_cselect_b32 s0, s0, 0
	v_readfirstlane_b32 s4, v0
	s_add_i32 s0, s4, s0
	s_mul_i32 s4, s0, s18
	s_sub_i32 s4, s13, s4
	s_sext_i32_i16 s4, s4
	s_add_i32 s26, s12, s4
; #define LAS __attribute__((address_space(3)))
; __device__ __forceinline__ int opaque_tid() { int t = threadIdx.x; asm volatile("" : "+v"(t)); return t; }
; __device__ __forceinline__ void attn_phase(LAS unsigned char* lds, bf16_t* p5, const bf16_t* vt, const float* relb, const float* dalam, const float* subln, float lam_init, int ocol) {
;     const int tid = opaque_tid(), lane = tid & 63, wave = __builtin_amdgcn_readfirstlane(tid >> 6), lq = lane & 15, g4 = lane >> 4;
;     const int cc = wave & 1, rgi = wave >> 1;
;     LAS float* btab = (LAS float*)(lds + 2 * KBYTES + 2 * VBYTES);
	v_cvt_f32_ubyte0_e32 v1, s19
	s_bfe_i64 s[4:5], s[0:1], 0x100000
	v_cvt_f32_i32_e32 v0, s3
	v_rcp_iflag_f32_e32 v2, v1
	s_lshl_b64 s[4:5], s[4:5], 20
	v_writelane_b32 v253, s4, 48
	s_ashr_i32 s27, s26, 31
	v_mul_f32_e32 v2, v0, v2
	v_writelane_b32 v253, s5, 49
	s_ashr_i32 s4, s3, 30
	s_or_b32 s12, s4, 1
	s_mov_b32 s4, s26
	v_writelane_b32 v253, s4, 50
	v_trunc_f32_e32 v2, v2
	v_fma_f32 v0, -v2, v1, v0
	v_writelane_b32 v253, s5, 51
	s_lshl_b64 s[4:5], s[26:27], 20
	v_writelane_b32 v253, s4, 52
	s_sext_i32_i16 s0, s0
	s_movk_i32 s27, 0xefc0
	v_writelane_b32 v253, s5, 53
	v_cmp_ge_f32_e64 s[4:5], |v0|, v1
	v_cvt_i32_f32_e32 v0, v2
	s_and_b64 s[4:5], s[4:5], exec
	s_cselect_b32 s4, s12, 0
	v_cvt_f32_ubyte0_e32 v1, s22
	v_readfirstlane_b32 s5, v0
	s_add_i32 s4, s5, s4
	s_mul_i32 s5, s4, s19
	s_sub_i32 s3, s3, s5
	s_sext_i32_i8 s3, s3
	s_add_i32 s3, s14, s3
	s_bfe_i64 s[12:13], s[4:5], 0x80000
	v_writelane_b32 v253, s3, 54
	s_lshl_b64 s[12:13], s[12:13], 19
	v_writelane_b32 v253, s12, 55
	s_cmp_gt_i32 s1, 0
	s_mul_i32 s3, s64, s1
	v_writelane_b32 v253, s13, 56
	s_cselect_b64 s[12:13], -1, 0
	v_writelane_b32 v253, s12, 57
	s_cmp_lt_i32 s1, 1
	s_mul_i32 s3, s3, -3
	v_writelane_b32 v253, s13, 58
	s_cselect_b64 s[12:13], -1, 0
	s_add_i32 s3, s3, s2
	v_writelane_b32 v253, s12, 59
	s_cmpk_lt_i32 s3, 0x60
	s_mul_hi_i32 s5, s3, 0x2aaaaaab
	v_writelane_b32 v253, s13, 60
	s_cselect_b64 s[12:13], -1, 0
	v_writelane_b32 v253, s12, 61
	v_rcp_iflag_f32_e32 v2, v1
	s_mul_i32 s1, s1, 3
	v_writelane_b32 v253, s13, 62
	s_lshr_b32 s12, s5, 31
	s_ashr_i32 s5, s5, 1
	s_add_i32 s5, s5, s12
	v_writelane_b32 v253, s5, 63
	s_mul_i32 s5, s5, -12
	s_add_i32 s3, s5, s3
	s_abs_i32 s5, s20
	v_cvt_f32_u32_e32 v0, s5
	s_sub_i32 s12, 0, s5
	s_mov_b32 s26, 0x437f0000
	v_rcp_iflag_f32_e32 v0, v0
	s_nop 0
	v_mul_f32_e32 v0, 0x4f7ffffe, v0
	v_cvt_u32_f32_e32 v0, v0
	s_nop 0
	v_readfirstlane_b32 s13, v0
	s_mul_i32 s12, s12, s13
	s_mul_hi_u32 s12, s13, s12
	s_add_i32 s13, s13, s12
	s_abs_i32 s12, s16
	s_mul_hi_u32 s14, s12, s13
	s_mul_i32 s13, s14, s5
	s_sub_i32 s18, s12, s13
	s_ashr_i32 s12, s3, 31
	s_lshr_b32 s12, s12, 30
	s_add_i32 s12, s3, s12
	s_ashr_i32 s13, s12, 2
	s_and_b32 s12, s12, -4
	s_sub_i32 s12, s3, s12
	s_lshl_b32 s3, s12, 2
	s_add_i32 s3, s3, 4
	v_writelane_b32 v254, s13, 0
	s_or_b32 s3, s3, s13
	s_ashr_i32 s13, s12, 31
	v_writelane_b32 v254, s3, 1
	s_lshl_b64 s[12:13], s[12:13], 9
	v_writelane_b32 v254, s12, 2
	s_xor_b32 s3, s16, s20
	s_ashr_i32 s3, s3, 31
	v_writelane_b32 v254, s13, 3
	s_add_i32 s12, s14, 1
	s_sub_i32 s13, s18, s5
	s_cmp_ge_u32 s18, s5
	s_cselect_b32 s12, s12, s14
	s_cselect_b32 s13, s13, s18
	s_add_i32 s14, s12, 1
	v_cvt_f32_i32_e32 v0, s17
	s_cmp_ge_u32 s13, s5
	s_cselect_b32 s5, s14, s12
	s_xor_b32 s5, s5, s3
	s_sub_i32 s3, s5, s3
	v_mul_f32_e32 v2, v0, v2
	v_writelane_b32 v254, s3, 4
	s_mul_i32 s3, s3, s20
	v_trunc_f32_e32 v2, v2
	s_sub_i32 s3, s16, s3
	v_fma_f32 v0, -v2, v1, v0
	s_add_i32 s3, s15, s3
	v_cmp_ge_f32_e64 s[12:13], |v0|, v1
	v_cvt_i32_f32_e32 v0, v2
	v_writelane_b32 v254, s3, 5
	s_ashr_i32 s3, s17, 30
	s_or_b32 s3, s3, 1
	s_and_b64 s[12:13], s[12:13], exec
	v_writelane_b32 v254, s0, 6
	s_sext_i32_i8 s0, s4
	v_writelane_b32 v254, s0, 7
	s_cselect_b32 s0, s3, 0
	v_readfirstlane_b32 s3, v0
	s_add_i32 s0, s3, s0
	s_mul_i32 s3, s0, s22
	s_sub_i32 s3, s17, s3
	v_writelane_b32 v254, s1, 8
	s_sext_i32_i16 s1, s3
	s_add_i32 s4, s21, s1
	s_sext_i32_i16 s1, s0
	v_writelane_b32 v254, s1, 9
	s_bfe_i64 s[0:1], s[0:1], 0x100000
	s_lshl_b64 s[0:1], s[0:1], 20
	v_writelane_b32 v254, s0, 10
	s_load_dword s5, s[24:25], 0x100
	s_ashr_i32 s71, s70, 31
	v_writelane_b32 v254, s1, 11
	s_add_i32 s0, s51, 0xffffc000
	v_writelane_b32 v254, s0, 12
	s_lshl_b32 s0, s2, 12
	v_writelane_b32 v254, s0, 13
	s_lshl_b32 s0, s64, 12
	v_writelane_b32 v254, s0, 14
	s_lshl_b32 s0, s2, 6
	v_writelane_b32 v254, s0, 15
	s_add_i32 s0, 0, 0x6200
	v_writelane_b32 v254, s0, 16
	s_add_i32 s0, 0, 0x4200
	v_writelane_b32 v254, s0, 17
	s_add_i32 s0, 0, 0x20200
	v_writelane_b32 v254, s0, 18
	s_add_i32 s0, 0, 0x20204
	v_writelane_b32 v254, s0, 19
	s_add_i32 s0, 0, 0x16000
	v_writelane_b32 v254, s0, 20
	s_add_i32 s0, 0, 0x19e34
	v_writelane_b32 v254, s0, 21
	s_mov_b32 s0, s4
	s_waitcnt lgkmcnt(0)
	s_mul_i32 s65, s65, s5
	s_ashr_i32 s5, s4, 31
	v_writelane_b32 v254, s0, 22
	s_lshl_b32 s35, s64, 6
	v_mov_b32_e32 v1, 0
	v_writelane_b32 v254, s1, 23
	s_lshl_b64 s[0:1], s[4:5], 20
	s_load_dwordx2 s[4:5], s[24:25], 0xf0
	v_writelane_b32 v254, s0, 24
	s_mov_b32 s3, 0x21000000
	s_mov_b64 s[20:21], 0x800
	v_writelane_b32 v254, s1, 25
	s_lshl_b64 s[0:1], s[70:71], 1
	v_writelane_b32 v254, s0, 26
	s_movk_i32 s71, 0x1ff
	s_mov_b64 s[22:23], 0x80
	v_writelane_b32 v254, s1, 27
	s_waitcnt lgkmcnt(0)
	v_writelane_b32 v254, s4, 28
	s_mov_b64 s[0:1], -1
	s_mov_b64 s[12:13], 0x14000
	v_writelane_b32 v254, s5, 29
	v_writelane_b32 v254, s24, 30
	s_load_dwordx4 s[16:19], s[24:25], 0x0
	s_nop 0
	v_writelane_b32 v254, s25, 31
	s_mov_b32 s24, 0
	s_waitcnt lgkmcnt(0)
	v_writelane_b32 v254, s16, 32
	s_nop 1
	v_writelane_b32 v254, s17, 33
	v_writelane_b32 v254, s18, 34
	v_writelane_b32 v254, s19, 35
	v_writelane_b32 v254, s94, 36
	s_nop 1
	v_writelane_b32 v254, s95, 37
	v_writelane_b32 v254, s96, 38
	s_nop 1
	v_writelane_b32 v254, s97, 39
	v_writelane_b32 v254, s90, 40
	s_nop 1
	v_writelane_b32 v254, s91, 41
	v_writelane_b32 v254, s88, 42
	s_nop 1
	v_writelane_b32 v254, s89, 43
	v_writelane_b32 v254, s92, 44
	s_nop 1
	v_writelane_b32 v254, s93, 45
	v_writelane_b32 v254, s74, 46
	s_nop 1
	v_writelane_b32 v254, s75, 47
	v_writelane_b32 v254, s51, 48
	v_writelane_b32 v254, s35, 49
	v_writelane_b32 v254, s52, 50
	s_branch .LBB0_23

; __device__ __forceinline__ void attn_phase(LAS unsigned char* lds, bf16_t* p5, const bf16_t* vt, const float* relb, const float* dalam, const float* subln, float lam_init, int ocol) {
;     ...
;     float lam;
;     { float s1 = 0.f, s2 = 0.f; for (int i = 0; i < 64; ++i) { s1 += dalam[i] * dalam[64 + i]; s2 += dalam[128 + i] * dalam[192 + i]; } lam = expf(s1) - expf(s2) + lam_init; }
.LBB0_640:
	s_add_u32 s14, s16, s4
	s_addc_u32 s15, s17, s5
	global_load_dwordx4 v[6:9], v1, s[14:15] offset:48
	global_load_dwordx4 v[10:13], v1, s[14:15] offset:32
	global_load_dwordx4 v[14:17], v1, s[14:15] offset:16
	global_load_dwordx4 v[18:21], v1, s[14:15]
	global_load_dwordx4 v[22:25], v1, s[14:15] offset:304
	global_load_dwordx4 v[26:29], v1, s[14:15] offset:288
	global_load_dwordx4 v[30:33], v1, s[14:15] offset:272
	global_load_dwordx4 v[34:37], v1, s[14:15] offset:256
	global_load_dwordx4 v[38:41], v1, s[14:15] offset:560
	global_load_dwordx4 v[42:45], v1, s[14:15] offset:544
	global_load_dwordx4 v[46:49], v1, s[14:15] offset:528
	global_load_dwordx4 v[50:53], v1, s[14:15] offset:512
	global_load_dwordx4 v[54:57], v1, s[14:15] offset:816
	global_load_dwordx4 v[58:61], v1, s[14:15] offset:800
	global_load_dwordx4 v[62:65], v1, s[14:15] offset:784
	global_load_dwordx4 v[66:69], v1, s[14:15] offset:768
	s_add_u32 s4, s4, 64
	s_addc_u32 s5, s5, 0
	s_cmpk_eq_i32 s4, 0x100
	s_waitcnt vmcnt(0)
	v_mov_b32_e32 v70, v18
	v_mov_b32_e32 v18, v20
	v_mov_b32_e32 v20, v30
	v_mov_b32_e32 v72, v34
	v_mov_b32_e32 v34, v36
	v_mov_b32_e32 v71, v50
	v_mov_b32_e32 v50, v19
	v_mov_b32_e32 v19, v52
	v_mov_b32_e32 v52, v21
	v_mov_b32_e32 v73, v66
	v_pk_fma_f32 v[2:3], v[70:71], v[72:73], v[2:3]
	v_mov_b32_e32 v66, v35
	v_pk_fma_f32 v[2:3], v[50:51], v[66:67], v[2:3]
	v_mov_b32_e32 v35, v68
	v_pk_fma_f32 v[2:3], v[18:19], v[34:35], v[2:3]
	v_mov_b32_e32 v68, v37
	v_pk_fma_f32 v[2:3], v[52:53], v[68:69], v[2:3]
	v_mov_b32_e32 v18, v14
	v_mov_b32_e32 v19, v46
	v_mov_b32_e32 v21, v62
	v_pk_fma_f32 v[2:3], v[18:19], v[20:21], v[2:3]
	v_mov_b32_e32 v46, v15
	v_mov_b32_e32 v62, v31
	v_pk_fma_f32 v[2:3], v[46:47], v[62:63], v[2:3]
	v_mov_b32_e32 v14, v16
	v_mov_b32_e32 v15, v48
	v_mov_b32_e32 v18, v32
	v_mov_b32_e32 v19, v64
	v_pk_fma_f32 v[2:3], v[14:15], v[18:19], v[2:3]
	v_mov_b32_e32 v48, v17
	v_mov_b32_e32 v64, v33
	v_pk_fma_f32 v[2:3], v[48:49], v[64:65], v[2:3]
	v_mov_b32_e32 v14, v10
	v_mov_b32_e32 v15, v42
	v_mov_b32_e32 v16, v26
	v_mov_b32_e32 v17, v58
	v_pk_fma_f32 v[2:3], v[14:15], v[16:17], v[2:3]
	v_mov_b32_e32 v42, v11
	v_mov_b32_e32 v58, v27
	v_pk_fma_f32 v[2:3], v[42:43], v[58:59], v[2:3]
	v_mov_b32_e32 v10, v12
	v_mov_b32_e32 v11, v44
	v_mov_b32_e32 v14, v28
	v_mov_b32_e32 v15, v60
	v_pk_fma_f32 v[2:3], v[10:11], v[14:15], v[2:3]
	v_mov_b32_e32 v44, v13
	v_mov_b32_e32 v60, v29
	v_pk_fma_f32 v[2:3], v[44:45], v[60:61], v[2:3]
	v_mov_b32_e32 v10, v6
	v_mov_b32_e32 v11, v38
	v_mov_b32_e32 v12, v22
	v_mov_b32_e32 v13, v54
	v_pk_fma_f32 v[2:3], v[10:11], v[12:13], v[2:3]
	v_mov_b32_e32 v38, v7
	v_mov_b32_e32 v54, v23
	v_pk_fma_f32 v[2:3], v[38:39], v[54:55], v[2:3]
	v_mov_b32_e32 v6, v8
	v_mov_b32_e32 v7, v40
	v_mov_b32_e32 v10, v24
	v_mov_b32_e32 v11, v56
	v_pk_fma_f32 v[2:3], v[6:7], v[10:11], v[2:3]
	v_mov_b32_e32 v40, v9
	v_mov_b32_e32 v56, v25
	v_pk_fma_f32 v[2:3], v[40:41], v[56:57], v[2:3]
	s_cbranch_scc0 .LBB0_640
; __device__ __forceinline__ void attn_phase(LAS unsigned char* lds, bf16_t* p5, const bf16_t* vt, const float* relb, const float* dalam, const float* subln, float lam_init, int ocol) {
;     ...
;     { float s1 = 0.f, s2 = 0.f; for (int i = 0; i < 64; ++i) { s1 += dalam[i] * dalam[64 + i]; s2 += dalam[128 + i] * dalam[192 + i]; } lam = expf(s1) - expf(s2) + lam_init; }
;     const int c = blockIdx.x, G = gridDim.x;
;     const float sc2 = 0.125f * LOG2E;
;     for (int r = 0;; ++r) {
;         const int idx = (r & 1) ? r * G + (G - 1 - c) : r * G + c;
;         if (r * G >= 33 * 32) break;
;         if (idx >= 33 * 32) continue;
;         const int qt = 32 - idx / 32, bh = idx & 31, b = bh >> 3, h = bh & 7;
;         const int njt = (2 * qt + 2) < 65 ? (2 * qt + 2) : 65;
;         const int qrow0 = qt * 128 + rgi * 32;
;         __syncthreads();
;         if (tid < 128) { const int d = tid; int bk = d; if (d >= 16) { bk = 16 + (int)(logf((float)d * (1.0f / 16.0f)) * (16.0f / logf(8.0f))); if (bk > 31) bk = 31; } btab[d] = relb[bk * 8 + h] * LOG2E; }
;         const float bfar = relb[31 * 8 + h] * LOG2E;
	v_cvt_f32_u32_e32 v0, s40
	s_mov_b32 s16, 0x800000
	s_add_u32 s4, s18, 0x8900000
	s_addc_u32 s5, s19, 0
	v_mul_f32_e32 v0, 0xbe99999a, v0
	v_mul_f32_e32 v5, 0x3fb8aa3b, v0
	v_fma_f32 v6, v0, s78, -v5
	v_rndne_f32_e32 v7, v5
	v_fmac_f32_e32 v6, 0x32a5705f, v0
	v_sub_f32_e32 v5, v5, v7
	v_add_f32_e32 v5, v5, v6
	v_cvt_i32_f32_e32 v7, v7
	v_exp_f32_e32 v5, v5
	v_cmp_ngt_f32_e32 vcc, s79, v0
	s_lshl_b64 s[14:15], s[40:41], 9
	s_add_u32 s24, s46, s14
	v_ldexp_f32 v5, v5, v7
	v_cndmask_b32_e32 v5, 0, v5, vcc
	v_cmp_nlt_f32_e32 vcc, s80, v0
	v_and_b32_e32 v141, 15, v4
	s_addc_u32 s25, s47, s15
	v_cndmask_b32_e32 v0, v216, v5, vcc
	v_mov_b32_e32 v5, 0x3f4ccccd
	v_fmamk_f32 v5, v0, 0xbf19999a, v5
	v_mul_f32_e32 v0, 0x3fb8aa3b, v2
	v_rndne_f32_e32 v6, v0
	v_sub_f32_e32 v7, v0, v6
	v_fma_f32 v0, v2, s78, -v0
	v_fmac_f32_e32 v0, 0x32a5705f, v2
	v_add_f32_e32 v0, v7, v0
	v_exp_f32_e32 v0, v0
	v_cvt_i32_f32_e32 v6, v6
	v_cmp_ngt_f32_e32 vcc, s79, v2
	v_and_b32_e32 v7, 63, v4
	v_bfe_u32 v8, v4, 4, 2
	v_ldexp_f32 v0, v0, v6
	v_mul_f32_e32 v6, 0x3fb8aa3b, v3
	v_rndne_f32_e32 v9, v6
	v_sub_f32_e32 v10, v6, v9
	v_fma_f32 v6, v3, s78, -v6
	v_fmac_f32_e32 v6, 0x32a5705f, v3
	v_add_f32_e32 v6, v10, v6
	v_exp_f32_e32 v6, v6
	v_cvt_i32_f32_e32 v9, v9
	v_cndmask_b32_e32 v0, 0, v0, vcc
	v_cmp_nlt_f32_e32 vcc, s80, v2
	v_lshl_add_u32 v10, v7, 4, 0
	v_ldexp_f32 v2, v6, v9
	v_cvt_f32_u32_e32 v6, v4
	v_cndmask_b32_e32 v0, v216, v0, vcc
	v_cmp_ngt_f32_e32 vcc, s79, v3
	v_mov_b32_e32 v7, v1
	v_ashrrev_i32_e32 v180, 4, v4
	v_cndmask_b32_e32 v2, 0, v2, vcc
	v_cmp_nlt_f32_e32 vcc, s80, v3
	v_mul_f32_e32 v3, 0x3d800000, v6
	s_bfe_u32 s14, s28, 0x10006
	v_cndmask_b32_e32 v2, v216, v2, vcc
	v_cmp_gt_f32_e32 vcc, s16, v3
	v_sub_f32_e32 v0, v0, v2
	v_add_f32_e32 v9, v5, v0
	v_cndmask_b32_e64 v6, 0, 32, vcc
	v_ldexp_f32 v3, v3, v6
	v_log_f32_e32 v3, v3
	s_mov_b32 s16, 0x3f317217
	v_mov_b32_e32 v2, 0x41b17218
	v_cndmask_b32_e32 v2, 0, v2, vcc
	v_mul_f32_e32 v0, 0x3f317217, v3
	v_fma_f32 v0, v3, s16, -v0
	v_fmac_f32_e32 v0, 0x3377d1cf, v3
	s_mov_b32 s16, 0x7f800000
	v_fmac_f32_e32 v0, 0x3f317217, v3
	v_cmp_lt_f32_e64 s[42:43], |v3|, s16
	v_cmp_lt_i32_e32 vcc, 15, v4
	v_readlane_b32 s16, v254, 20
	v_cndmask_b32_e64 v0, v3, v0, s[42:43]
	v_sub_f32_e32 v0, v0, v2
	v_mul_f32_e32 v0, 0x40f6384f, v0
	v_cvt_i32_f32_e32 v0, v0
	v_cmp_gt_i32_e64 s[42:43], s77, v4
	v_lshl_add_u32 v143, v4, 2, s16
	s_lshl_b32 s16, s14, 7
	v_min_i32_e32 v0, 15, v0
	v_add_u32_e32 v3, 16, v0
	v_lshlrev_b32_e32 v0, 3, v4
	v_and_b32_e32 v2, 0x78, v0
	v_lshlrev_b32_e32 v0, 4, v4
	v_and_b32_e32 v6, 0xf0, v0
	v_cndmask_b32_e32 v3, v4, v3, vcc
	v_add_u32_e32 v165, 0, v6
	v_and_b32_e32 v6, 0x70, v0
	v_and_b32_e32 v0, 48, v4
	v_lshlrev_b32_e32 v179, 3, v3
	v_ashrrev_i32_e32 v3, 3, v4
	v_add_u32_e32 v4, 0x200, v4
	v_add_u32_e32 v174, 0, v6
	v_lshl_add_u64 v[144:145], s[24:25], 0, v[0:1]
	v_lshl_add_u64 v[6:7], s[18:19], 0, v[6:7]
	s_mov_b64 s[18:19], 0x21000000
	s_movk_i32 s24, 0x2080
	v_ashrrev_i32_e32 v181, 4, v4
	v_ashrrev_i32_e32 v4, 3, v4
	v_lshl_add_u64 v[146:147], v[6:7], 0, s[18:19]
	v_mad_i64_i32 v[150:151], s[18:19], v3, s24, 0
	v_mad_i64_i32 v[154:155], s[18:19], v4, s24, 0
	s_movk_i32 s24, 0x90
	s_ashr_i32 s15, s28, 7
	s_add_i32 s16, s16, 0
	v_mad_i64_i32 v[148:149], s[18:19], v180, s84, 0
	v_mad_i64_i32 v[152:153], s[18:19], v181, s84, 0
	v_mul_lo_u32 v183, v3, s24
	v_mov_b32_e32 v3, 0x900
	s_lshl_b32 s40, s15, 5
	s_lshl_b32 s29, s14, 6
	v_add_u32_e32 v175, s16, v0
	s_lshl_b32 s30, s15, 14
	s_and_b32 s16, 64, s28
	s_movk_i32 s18, 0x110
	v_mad_u32_u24 v187, v141, s24, v3
	v_add_u32_e32 v3, 64, v180
	s_cmp_eq_u32 s14, 0
	v_mul_lo_u32 v182, v180, s18
	v_mul_lo_u32 v184, v181, s18
	v_mad_i64_i32 v[156:157], s[18:19], v3, s84, 0
	v_add_u32_e32 v3, 64, v181
	s_cselect_b64 s[14:15], -1, 0
	s_cmp_lg_u32 s16, 0
	v_mad_i64_i32 v[158:159], s[18:19], v3, s84, 0
	s_cselect_b64 s[16:17], -1, 0
	s_and_b32 s18, s28, 0xffffff80
	v_sub_f32_e32 v178, 1.0, v5
	v_lshl_or_b32 v5, v141, 2, s18
	v_sub_u32_e32 v0, v5, v0
	v_readlane_b32 s18, v254, 21
	v_lshlrev_b32_e32 v140, 3, v8
	v_mad_u32_u24 v188, v141, s24, 0
	v_add_u32_e32 v193, s18, v0
	s_add_i32 s18, s40, 0xfd0
	v_mul_u32_u24_e32 v176, 0x90, v141
	v_lshlrev_b32_e32 v142, 2, v8
	v_mul_lo_u32 v185, v4, s24
	v_add_u32_e32 v3, 0, v140
	v_add_u32_e32 v4, 0x900, v188
	v_or_b32_e32 v0, s18, v141
	s_mov_b32 s41, 0
	v_cndmask_b32_e64 v177, v9, 1.0, s[14:15]
	v_mul_u32_u24_e32 v186, 0x110, v141
	v_or_b32_e32 v189, 48, v142
	v_or_b32_e32 v190, 49, v142
	v_or_b32_e32 v191, 50, v142
	v_or_b32_e32 v192, 51, v142
	v_sub_u32_e32 v194, v0, v142
	s_lshl_b32 s18, s29, 1
	v_lshlrev_b32_e32 v160, 1, v2
	v_add_u32_e32 v195, v3, v176
	v_add_u32_e32 v196, v4, v140
	v_add_u32_e32 v197, s30, v10
	s_movk_i32 s73, 0x1040
	s_bfe_u32 s52, s28, 0x10008
	s_branch .LBB0_643

; #define LAS __attribute__((address_space(3)))
; #define ATT_LOAD(j) do { _Pragma("unroll") for (int i = 0; i < 2; ++i) { const int id = tid + 512 * i; \
;             kreg[i] = *(const u32x4*)(kbase + (size_t)((j) * 64 + (id >> 4)) * LDP + (id & 15) * 8); \
;             vreg[i] = *(const u32x4*)(vbase + (size_t)(id >> 3) * TP + (j) * 64 + (id & 7) * 8); } } while (0)
; __device__ __forceinline__ void attn_phase(LAS unsigned char* lds, bf16_t* p5, const bf16_t* vt, const float* relb, const float* dalam, const float* subln, float lam_init, int ocol) {
;     ...
;         bf16x8 qf[2][2];
; #pragma unroll
;         for (int rg = 0; rg < 2; ++rg) { const int q = qrow0 + 16 * rg + lq, qc = q < TP ? q : TP - 1;
; #pragma unroll
;             for (int s = 0; s < 2; ++s) qf[rg][s] = *(const bf16x8*)(p5 + ((size_t)b * TP + qc) * LDP + C_Q + h * 128 + cc * 64 + s * 32 + 8 * g4); }
;         f32x4 O[2][8]; float mrow[2], lrow[2];
; #pragma unroll
;         for (int rg = 0; rg < 2; ++rg) { mrow[rg] = -INFINITY; lrow[rg] = 0.f;
; #pragma unroll
;             for (int k = 0; k < 8; ++k) O[rg][k] = (f32x4){0.f, 0.f, 0.f, 0.f}; }
;         u32x4 kreg[2], vreg[2];
;         const bf16_t* kbase = p5 + (size_t)b * TP * LDP + C_K + h * 128; const bf16_t* vbase = vt + (size_t)bh * 128 * TP;
;     ...
;         ATT_LOAD(0); ATT_STORE(0); __syncthreads();
;         for (int j = 0; j < njt; ++j) {
;             if (j + 1 < njt) ATT_LOAD(j + 1);
;             if (j * 64 <= qrow0 + 31) {
;                 const LAS unsigned char* kb_ = lds + (j & 1) * KBYTES; const LAS unsigned char* vb_ = lds + 2 * KBYTES + (j & 1) * VBYTES;
;                 bf16x8 kf[4][2];
; #pragma unroll
;                 for (int kb = 0; kb < 4; ++kb)
; #pragma unroll
;                     for (int s = 0; s < 2; ++s) kf[kb][s] = *(const LAS bf16x8*)(kb_ + (16 * kb + lq) * KPITCH + (cc * 64 + s * 32 + 8 * g4) * 2);
;                 __builtin_amdgcn_sched_barrier(0);
;                 f32x4 st[2][4];
; #pragma unroll
;                 for (int kb = 0; kb < 4; ++kb)
; #pragma unroll
;                     for (int rg = 0; rg < 2; ++rg) { f32x4 a = (f32x4){0.f, 0.f, 0.f, 0.f};
; #pragma unroll
;                         for (int s = 0; s < 2; ++s) a = __builtin_amdgcn_mfma_f32_16x16x32_bf16(kf[kb][s], qf[rg][s], a, 0, 0, 0);
.LBB0_647:
	s_or_b64 exec, exec, s[24:25]
	s_ashr_i32 s24, s19, 31
	s_lshr_b32 s24, s24, 27
	s_add_i32 s24, s19, s24
	s_ashr_i32 s34, s24, 5
	s_sub_i32 s31, 32, s34
	s_lshl_b32 s46, s31, 7
	s_add_i32 s46, s46, s40
	v_or_b32_e32 v168, s46, v141
	s_and_b32 s35, s19, 31
	s_bfe_u32 s19, s19, 0x20003
	v_min_i32_e32 v2, 0x103f, v168
	s_mul_i32 s24, s19, 0x1040
	s_mov_b32 s25, s69
	v_ashrrev_i32_e32 v3, 31, v2
	v_lshl_add_u64 v[2:3], v[2:3], 0, s[24:25]
	v_mov_b64_e32 v[4:5], s[4:5]
	v_mad_u64_u32 v[6:7], s[28:29], v2, s84, v[4:5]
	v_mad_i32_i24 v7, v3, s84, v7
	s_lshl_b32 s68, s30, 8
	v_or_b32_e32 v166, 16, v168
	v_lshl_add_u64 v[2:3], v[6:7], 0, s[68:69]
	v_min_i32_e32 v6, 0x103f, v166
	v_ashrrev_i32_e32 v7, 31, v6
	s_lshl_b32 s44, s30, 2
	v_lshl_add_u64 v[6:7], v[6:7], 0, s[24:25]
	s_mul_i32 s19, s19, 0x28a0000
	v_mad_u64_u32 v[4:5], s[28:29], v6, s84, v[4:5]
	s_add_u32 s19, s4, s19
	s_addc_u32 s29, s5, 0
	s_add_u32 s28, s19, s68
	s_addc_u32 s29, s29, 0
	v_mov_b32_e32 v161, v1
	v_mad_i32_i24 v5, v7, s84, v5
	v_lshl_add_u64 v[6:7], s[28:29], 0, v[160:161]
	s_mov_b64 s[28:29], 0x1800
	v_lshl_add_u64 v[4:5], v[4:5], 0, s[68:69]
	v_lshl_add_u64 v[170:171], v[6:7], 0, s[28:29]
	s_mul_i32 s68, s35, 0x104000
	v_lshl_add_u64 v[172:173], v[146:147], 0, s[68:69]
	v_lshl_add_u64 v[6:7], v[170:171], 0, v[148:149]
	global_load_dwordx4 v[20:23], v[6:7], off
	v_lshl_add_u64 v[36:37], v[172:173], 0, v[150:151]
	global_load_dwordx4 v[24:27], v[36:37], off
	v_lshl_add_u64 v[6:7], v[170:171], 0, v[152:153]
	global_load_dwordx4 v[28:31], v[6:7], off
	v_lshl_add_u64 v[38:39], v[172:173], 0, v[154:155]
	global_load_dwordx4 v[32:35], v[38:39], off
	s_mov_b32 s19, s69
	v_lshlrev_b32_e32 v0, 1, v140
	v_lshl_add_u64 v[2:3], v[2:3], 0, s[18:19]
	v_lshl_add_u64 v[2:3], v[2:3], 0, v[0:1]
	v_lshl_add_u64 v[4:5], v[4:5], 0, s[18:19]
	s_mov_b64 s[28:29], 0x1000
	s_movk_i32 s19, 0x1000
	v_lshl_add_u64 v[8:9], v[2:3], 0, s[28:29]
	v_add_co_u32_e32 v2, vcc, s19, v2
	v_mov_b32_e32 v6, s44
	s_nop 0
	v_addc_co_u32_e32 v3, vcc, 0, v3, vcc
	v_lshl_add_u64 v[12:13], v[4:5], 0, v[0:1]
	global_load_dword v44, v6, s[0:1] offset:992
	s_nop 0
	global_load_dwordx4 v[4:7], v[2:3], off
	s_nop 0
	global_load_dwordx4 v[8:11], v[8:9], off offset:64
	v_lshl_add_u64 v[2:3], v[12:13], 0, s[28:29]
	v_add_co_u32_e32 v12, vcc, s19, v12
	v_add_u32_e32 v100, v165, v182
	v_lshl_add_u64 v[40:41], v[170:171], 0, v[156:157]
	v_addc_co_u32_e32 v13, vcc, 0, v13, vcc
	v_add_u32_e32 v101, v174, v183
	v_add_u32_e32 v102, v165, v184
	v_add_u32_e32 v103, v174, v185
	v_lshl_add_u64 v[42:43], v[170:171], 0, v[158:159]
	global_load_dwordx4 v[12:15], v[12:13], off
	s_nop 0
	global_load_dwordx4 v[16:19], v[2:3], off offset:64
	s_cmp_lt_i32 s46, 0
	s_waitcnt vmcnt(8)
	ds_write_b128 v100, v[20:23]
	s_waitcnt vmcnt(7)
	ds_write_b128 v101, v[24:27] offset:34816
	s_waitcnt vmcnt(6)
	ds_write_b128 v102, v[28:31]
	s_waitcnt vmcnt(5)
	ds_write_b128 v103, v[32:35] offset:34816
	s_waitcnt lgkmcnt(0)
	s_barrier
	global_load_dwordx4 v[20:23], v[40:41], off
	global_load_dwordx4 v[28:31], v[42:43], off
	global_load_dwordx4 v[24:27], v[36:37], off offset:128
	global_load_dwordx4 v[32:35], v[38:39], off offset:128
	s_waitcnt vmcnt(8)
	v_mul_f32_e32 v222, 0x3fb8aa3b, v44
	s_cbranch_scc1 .LBB0_665
	v_add_u32_e32 v0, v175, v186
	ds_read_b128 v[36:39], v0 offset:13056
	ds_read_b128 v[40:43], v0 offset:13120
	s_waitcnt vmcnt(7) lgkmcnt(1)
	v_mfma_f32_16x16x32_bf16 v[44:47], v[36:39], v[4:7], 0
	s_waitcnt vmcnt(5)
	v_mfma_f32_16x16x32_bf16 v[36:39], v[36:39], v[12:15], 0
	s_waitcnt lgkmcnt(0)
	v_mfma_f32_16x16x32_bf16 v[48:51], v[40:43], v[8:11], v[44:47]
	s_waitcnt vmcnt(4)
	v_mfma_f32_16x16x32_bf16 v[44:47], v[40:43], v[16:19], v[36:39]
	v_add_u32_e32 v2, v188, v140
	v_add_u32_e32 v0, 0x8800, v2
	ds_read2_b64 v[40:43], v0 offset1:4
	s_nop 0
	ds_read2_b64 v[36:39], v0 offset0:8 offset1:12
	v_sub_u32_e32 v0, v168, v189
	v_cmp_gt_u32_e32 vcc, s77, v0
	v_mov_b32_e32 v3, v222
	s_and_saveexec_b64 s[28:29], vcc
	v_lshl_add_u32 v3, v0, 2, 0
	v_add_u32_e32 v3, 0x16000, v3
	ds_read_b32 v3, v3
	s_or_b64 exec, exec, s[28:29]
	v_sub_u32_e32 v52, v168, v190
	v_cmp_gt_u32_e32 vcc, s77, v52
	v_mov_b32_e32 v53, v222
	s_and_saveexec_b64 s[28:29], vcc
	v_lshl_add_u32 v53, v52, 2, 0
	v_add_u32_e32 v53, 0x16000, v53
	ds_read_b32 v53, v53
	s_or_b64 exec, exec, s[28:29]
	v_sub_u32_e32 v54, v168, v191
	v_cmp_gt_u32_e32 vcc, s77, v54
	v_mov_b32_e32 v55, v222
	s_and_saveexec_b64 s[28:29], vcc
	v_lshl_add_u32 v55, v54, 2, 0
	v_add_u32_e32 v55, 0x16000, v55
	ds_read_b32 v55, v55
	s_or_b64 exec, exec, s[28:29]
	v_sub_u32_e32 v56, v168, v192
	v_cmp_gt_u32_e32 vcc, s77, v56
	v_mov_b32_e32 v57, v222
	s_and_saveexec_b64 s[28:29], vcc
	v_lshl_add_u32 v57, v56, 2, 0
	v_add_u32_e32 v57, 0x16000, v57
	ds_read_b32 v57, v57
	s_or_b64 exec, exec, s[28:29]
	s_waitcnt lgkmcnt(0)
; __device__ __forceinline__ void attn_phase(LAS unsigned char* lds, bf16_t* p5, const bf16_t* vt, const float* relb, const float* dalam, const float* subln, float lam_init, int ocol) {
;     ...
;                         const int q = qrow0 + 16 * rg + lq;
; #pragma unroll
;                         for (int kb = 0; kb < 4; ++kb)
; #pragma unroll
;                             for (int i = 0; i < 4; ++i) { float v = st[rg][kb][i] * sc2;
;                                 const int kp = j * 64 + 16 * kb + 4 * g4 + i; const int dist = q - kp;
;                                 const float bv = (dist >= 0 && dist < 128) ? btab[dist] : bfar;
;                                 v = (kp >= PADT && dist >= 0) ? v + bv : -INFINITY;
;                                 st[rg][kb][i] = v; rmax = fmaxf(rmax, v); }
;                         rmax = rows4_max(rmax);
;                         const float mnew = fmaxf(mrow[rg], rmax); msafe = (mnew == -INFINITY) ? 0.f : mnew;
;                         alpha = __builtin_amdgcn_exp2f(mrow[rg] - msafe); mrow[rg] = mnew;
; #pragma unroll
;                         for (int kb = 0; kb < 4; ++kb)
; #pragma unroll
;                             for (int i = 0; i < 4; ++i) st[rg][kb][i] = __builtin_amdgcn_exp2f(st[rg][kb][i] - msafe);
;                     }
;                     float rs = 0.f;
; #pragma unroll
;                     for (int kb = 0; kb < 4; ++kb) rs += (st[rg][kb][0] + st[rg][kb][1]) + (st[rg][kb][2] + st[rg][kb][3]);
;                     lrow[rg] = lrow[rg] * alpha + rs;
;                     if (__builtin_amdgcn_ballot_w64(alpha != 1.0f) != 0ull) {
; #pragma unroll
;                         for (int k = 0; k < 8; ++k) O[rg][k] *= alpha; }
; #pragma unroll
;                     for (int s = 0; s < 2; ++s) { u32x4 w; w.x = cvt_pk_bf16(st[rg][2 * s][0], st[rg][2 * s][1]); w.y = cvt_pk_bf16(st[rg][2 * s][2], st[rg][2 * s][3]);
;                         w.z = cvt_pk_bf16(st[rg][2 * s + 1][0], st[rg][2 * s + 1][1]); w.w = cvt_pk_bf16(st[rg][2 * s + 1][2], st[rg][2 * s + 1][3]);
;                         pk[rg][s] = __builtin_bit_cast(bf16x8, w); }
;                 }
;                 __builtin_amdgcn_sched_barrier(0);
;                 u32x2 vc[3][2][2];
;                 ATT_VLOAD(vc, 1, 3)
;                 __builtin_amdgcn_sched_barrier(0);
;                 ATT_PV(va, 0, 1)
	v_fmac_f32_e32 v3, 0x3e38aa3b, v48
	v_cmp_lt_i32_e32 vcc, -1, v0
	v_fmac_f32_e32 v53, 0x3e38aa3b, v49
	v_fmac_f32_e32 v55, 0x3e38aa3b, v50
	v_cndmask_b32_e32 v3, v221, v3, vcc
	v_cmp_lt_i32_e32 vcc, -1, v52
	v_fmac_f32_e32 v57, 0x3e38aa3b, v51
	s_nop 0
	v_cndmask_b32_e32 v48, v221, v53, vcc
	v_cmp_lt_i32_e32 vcc, -1, v54
	v_max3_f32 v0, v3, s87, v48
	v_mov_b32_e32 v54, v222
	v_cndmask_b32_e32 v50, v221, v55, vcc
	v_cmp_lt_i32_e32 vcc, -1, v56
	s_nop 1
	v_cndmask_b32_e32 v49, v221, v57, vcc
	v_max3_f32 v0, v0, v50, v49
	v_mov_b32_e32 v51, v0
	s_nop 1
	v_permlane16_swap_b32_e32 v0, v51
	v_max_f32_e32 v51, v51, v51
	v_max_f32_e32 v0, v0, v0
	v_max_f32_e32 v0, v0, v51
	v_mov_b32_e32 v51, v0
	s_nop 1
	v_permlane32_swap_b32_e32 v0, v51
	v_max3_f32 v0, v0, v51, s87
	v_cmp_neq_f32_e32 vcc, s87, v0
	s_nop 1
	v_cndmask_b32_e32 v51, 0, v0, vcc
	v_sub_f32_e32 v48, v48, v51
	v_sub_f32_e32 v52, v49, v51
	v_exp_f32_e32 v49, v48
	v_sub_f32_e32 v48, 0xff800000, v51
	v_sub_f32_e32 v3, v3, v51
	v_exp_f32_e32 v48, v48
	v_sub_f32_e32 v50, v50, v51
	v_exp_f32_e32 v3, v3
	v_exp_f32_e32 v50, v50
	v_exp_f32_e32 v51, v52
	v_sub_u32_e32 v52, v166, v189
	v_cmp_neq_f32_e32 vcc, 1.0, v48
	v_cmp_gt_u32_e64 s[44:45], s77, v52
	v_cvt_pk_bf16_f32 v68, v48, v48
	v_cvt_pk_bf16_f32 v69, v48, v48
	v_cvt_pk_bf16_f32 v70, v48, v48
	v_cvt_pk_bf16_f32 v71, v48, v48
	v_cvt_pk_bf16_f32 v64, v48, v48
	v_cvt_pk_bf16_f32 v65, v48, v48
	v_cvt_pk_bf16_f32 v66, v3, v49
	v_cvt_pk_bf16_f32 v67, v50, v51
	s_and_saveexec_b64 s[28:29], s[44:45]
	v_lshl_add_u32 v53, v52, 2, 0
	v_add_u32_e32 v53, 0x16000, v53
	ds_read_b32 v54, v53
	s_or_b64 exec, exec, s[28:29]
	v_sub_u32_e32 v56, v166, v190
	v_cmp_gt_u32_e64 s[44:45], s77, v56
	v_mov_b32_e32 v57, v222
	s_and_saveexec_b64 s[28:29], s[44:45]
	v_lshl_add_u32 v53, v56, 2, 0
	v_add_u32_e32 v53, 0x16000, v53
	ds_read_b32 v57, v53
	s_or_b64 exec, exec, s[28:29]
	v_sub_u32_e32 v58, v166, v191
	v_cmp_gt_u32_e64 s[44:45], s77, v58
	v_mov_b32_e32 v59, v222
	s_and_saveexec_b64 s[28:29], s[44:45]
	v_lshl_add_u32 v53, v58, 2, 0
	v_add_u32_e32 v53, 0x16000, v53
	ds_read_b32 v59, v53
	s_or_b64 exec, exec, s[28:29]
	v_sub_u32_e32 v53, v166, v192
	v_cmp_gt_u32_e64 s[44:45], s77, v53
	v_mov_b32_e32 v55, v222
	s_and_saveexec_b64 s[28:29], s[44:45]
	v_lshl_add_u32 v55, v53, 2, 0
	v_add_u32_e32 v55, 0x16000, v55
	ds_read_b32 v55, v55
	s_or_b64 exec, exec, s[28:29]
	s_waitcnt lgkmcnt(0)
	v_fmac_f32_e32 v54, 0x3e38aa3b, v44
	v_cmp_lt_i32_e64 s[44:45], -1, v52
	v_fmac_f32_e32 v59, 0x3e38aa3b, v46
	v_add_f32_e32 v46, v48, v48
	v_cndmask_b32_e64 v44, v221, v54, s[44:45]
	v_cmp_lt_i32_e64 s[44:45], -1, v56
	v_fma_f32 v56, v46, 2.0, 0
	v_fmac_f32_e32 v56, 2.0, v46
	v_fmac_f32_e32 v56, 2.0, v46
	v_add_f32_e32 v3, v3, v49
	v_add_f32_e32 v46, v51, v50
	s_cmp_lg_u64 vcc, 0
	v_fmac_f32_e32 v57, 0x3e38aa3b, v45
	v_add_f32_e32 v3, v3, v46
	v_mul_f32_e32 v46, 0, v48
	s_cselect_b64 vcc, -1, 0
	v_cndmask_b32_e64 v45, v221, v57, s[44:45]
	v_cmp_lt_i32_e64 s[44:45], -1, v58
	v_cndmask_b32_e32 v104, 0, v46, vcc
	v_fmac_f32_e32 v55, 0x3e38aa3b, v47
	v_cmp_lt_i32_e32 vcc, -1, v53
	v_max3_f32 v52, v44, s87, v45
	v_cndmask_b32_e64 v54, v221, v59, s[44:45]
	v_cndmask_b32_e32 v46, v221, v55, vcc
	v_add_f32_e32 v3, v3, v56
	v_max3_f32 v47, v52, v54, v46
	v_fmac_f32_e32 v3, 0, v48
	v_mov_b32_e32 v48, v47
	s_nop 1
	v_permlane16_swap_b32_e32 v47, v48
	v_max_f32_e32 v48, v48, v48
	v_max_f32_e32 v47, v47, v47
	v_max_f32_e32 v47, v47, v48
	v_mov_b32_e32 v48, v47
	s_nop 1
	v_permlane32_swap_b32_e32 v47, v48
	v_max3_f32 v199, v47, v48, s87
	v_cmp_neq_f32_e32 vcc, s87, v199
	v_mov_b32_e32 v105, v104
	v_mov_b32_e32 v106, v104
	v_cndmask_b32_e32 v47, 0, v199, vcc
	v_sub_f32_e32 v45, v45, v47
	v_sub_f32_e32 v49, v46, v47
	v_exp_f32_e32 v46, v45
	v_sub_f32_e32 v45, 0xff800000, v47
	v_exp_f32_e32 v56, v45
	v_sub_f32_e32 v44, v44, v47
	v_sub_f32_e32 v45, v54, v47
	v_exp_f32_e32 v44, v44
	v_exp_f32_e32 v48, v45
	v_exp_f32_e32 v50, v49
	v_add_f32_e32 v51, v56, v56
	v_add_f32_e32 v47, v51, v51
	v_fma_f32 v45, v51, 2.0, 0
	v_mov_b32_e32 v49, v51
	v_pk_add_f32 v[52:53], v[44:45], v[46:47]
	v_pk_add_f32 v[54:55], v[50:51], v[48:49]
	v_cmp_neq_f32_e32 vcc, 1.0, v56
	v_pk_add_f32 v[52:53], v[52:53], v[54:55]
	s_cmp_lg_u64 vcc, 0
	v_add_f32_e32 v167, v52, v53
	v_mul_f32_e32 v45, 0, v56
	s_cselect_b64 vcc, -1, 0
	v_fmac_f32_e32 v167, 0, v56
	v_cndmask_b32_e32 v108, 0, v45, vcc
	v_mov_b32_e32 v107, v104
	v_mov_b32_e32 v109, v108
	v_mov_b32_e32 v110, v108
	v_mov_b32_e32 v111, v108
	v_cvt_pk_bf16_f32 v112, v56, v56
	v_cvt_pk_bf16_f32 v113, v56, v56
	v_cvt_pk_bf16_f32 v114, v56, v56
	v_cvt_pk_bf16_f32 v115, v56, v56
	v_cvt_pk_bf16_f32 v116, v56, v56
	v_cvt_pk_bf16_f32 v117, v56, v56
	v_cvt_pk_bf16_f32 v118, v44, v46
	v_cvt_pk_bf16_f32 v119, v48, v50
	v_add_u32_e32 v48, 0x9000, v195
	v_add_u32_e32 v56, 0x9800, v195
	ds_read2_b64 v[44:47], v48 offset0:32 offset1:36
	ds_read2_b64 v[48:51], v48 offset0:40 offset1:44
	ds_read2_b64 v[52:55], v56 offset0:64 offset1:68
	ds_read2_b64 v[60:63], v56 offset0:72 offset1:76
	v_add_u32_e32 v56, 0xa000, v195
	ds_read2_b64 v[72:75], v56 offset0:96 offset1:100
	ds_read2_b64 v[76:79], v56 offset0:104 offset1:108
	v_mfma_f32_16x16x32_bf16 v[56:59], v[40:43], v[68:71], v[104:107]
	v_mfma_f32_16x16x32_bf16 v[40:43], v[40:43], v[112:115], v[108:111]
	v_mfma_f32_16x16x32_bf16 v[88:91], v[36:39], v[64:67], v[56:59]
	v_mfma_f32_16x16x32_bf16 v[40:43], v[36:39], v[116:119], v[40:43]
	v_add_u32_e32 v36, 0xa800, v2
	ds_read2_b64 v[84:87], v36 offset0:128 offset1:132
	ds_read2_b64 v[120:123], v36 offset0:136 offset1:140
	v_add_u32_e32 v36, 0xa800, v196
	ds_read2_b64 v[124:127], v36 offset0:128 offset1:132
	ds_read2_b64 v[128:131], v36 offset0:136 offset1:140
	s_waitcnt lgkmcnt(9)
; #define ATT_VLOAD(dst, k0, nk) _Pragma("unroll") for (int k = 0; k < (nk); ++k) _Pragma("unroll") for (int s = 0; s < 2; ++s) { \
;                     const LAS unsigned char* vp = vb_ + (16 * (k + (k0)) + lq) * VPITCH + (32 * s + 4 * g4) * 2; dst[k][s][0] = *(const LAS u32x2*)vp; dst[k][s][1] = *(const LAS u32x2*)(vp + 32); }
; __device__ __forceinline__ void attn_phase(LAS unsigned char* lds, bf16_t* p5, const bf16_t* vt, const float* relb, const float* dalam, const float* subln, float lam_init, int ocol) {
;     ...
;                 u32x2 vc[3][2][2];
;                 ATT_VLOAD(vc, 1, 3)
;                 __builtin_amdgcn_sched_barrier(0);
;                 ATT_PV(va, 0, 1)
;                 __builtin_amdgcn_sched_barrier(0);
;                 u32x2 vd[2][2][2];
;                 ATT_VLOAD(vd, 4, 2)
;                 __builtin_amdgcn_sched_barrier(0);
;                 ATT_PV(vc, 1, 3)
;                 __builtin_amdgcn_sched_barrier(0);
;                 u32x2 ve[2][2][2];
;                 ATT_VLOAD(ve, 6, 2)
;                 __builtin_amdgcn_sched_barrier(0);
;                 ATT_PV(vd, 4, 2)
;                 __builtin_amdgcn_sched_barrier(0);
;                 ATT_PV(ve, 6, 2)
	v_mfma_f32_16x16x32_bf16 v[36:39], v[44:47], v[68:71], v[104:107]
	v_mfma_f32_16x16x32_bf16 v[44:47], v[44:47], v[112:115], v[108:111]
	s_waitcnt lgkmcnt(8)
	v_mfma_f32_16x16x32_bf16 v[92:95], v[48:51], v[64:67], v[36:39]
	v_mfma_f32_16x16x32_bf16 v[56:59], v[48:51], v[116:119], v[44:47]
	s_waitcnt lgkmcnt(7)
	v_mfma_f32_16x16x32_bf16 v[36:39], v[52:55], v[68:71], v[104:107]
	v_mfma_f32_16x16x32_bf16 v[44:47], v[52:55], v[112:115], v[108:111]
	s_waitcnt lgkmcnt(6)
	v_mfma_f32_16x16x32_bf16 v[80:83], v[60:63], v[64:67], v[36:39]
	v_mfma_f32_16x16x32_bf16 v[48:51], v[60:63], v[116:119], v[44:47]
	s_waitcnt lgkmcnt(5)
	v_mfma_f32_16x16x32_bf16 v[36:39], v[72:75], v[68:71], v[104:107]
	v_mfma_f32_16x16x32_bf16 v[44:47], v[72:75], v[112:115], v[108:111]
	s_waitcnt lgkmcnt(4)
	v_mfma_f32_16x16x32_bf16 v[72:75], v[76:79], v[64:67], v[36:39]
	v_mfma_f32_16x16x32_bf16 v[36:39], v[76:79], v[116:119], v[44:47]
	v_add_u32_e32 v2, 0xb800, v2
	s_nop 3
	ds_read2_b64 v[44:47], v2 offset0:192 offset1:196
	ds_read2_b64 v[132:135], v2 offset0:200 offset1:204
	v_add_u32_e32 v2, 0xb800, v196
	ds_read2_b64 v[136:139], v2 offset0:192 offset1:196
	ds_read2_b64 v[200:203], v2 offset0:200 offset1:204
	s_waitcnt lgkmcnt(7)
	v_mfma_f32_16x16x32_bf16 v[52:55], v[84:87], v[68:71], v[104:107]
	v_mfma_f32_16x16x32_bf16 v[60:63], v[84:87], v[112:115], v[108:111]
	s_waitcnt lgkmcnt(6)
	v_mfma_f32_16x16x32_bf16 v[96:99], v[120:123], v[64:67], v[52:55]
	s_waitcnt lgkmcnt(5)
	v_mfma_f32_16x16x32_bf16 v[52:55], v[124:127], v[68:71], v[104:107]
	v_mfma_f32_16x16x32_bf16 v[76:79], v[124:127], v[112:115], v[108:111]
	v_mfma_f32_16x16x32_bf16 v[60:63], v[120:123], v[116:119], v[60:63]
	s_waitcnt lgkmcnt(4)
	v_mfma_f32_16x16x32_bf16 v[84:87], v[128:131], v[64:67], v[52:55]
	v_mfma_f32_16x16x32_bf16 v[52:55], v[128:131], v[116:119], v[76:79]
	s_waitcnt lgkmcnt(3)
	v_mfma_f32_16x16x32_bf16 v[76:79], v[44:47], v[68:71], v[104:107]
	v_mfma_f32_16x16x32_bf16 v[44:47], v[44:47], v[112:115], v[108:111]
	s_waitcnt lgkmcnt(1)
	v_mfma_f32_16x16x32_bf16 v[68:71], v[136:139], v[68:71], v[104:107]
	v_mfma_f32_16x16x32_bf16 v[104:107], v[136:139], v[112:115], v[108:111]
	v_mfma_f32_16x16x32_bf16 v[76:79], v[132:135], v[64:67], v[76:79]
	v_mfma_f32_16x16x32_bf16 v[44:47], v[132:135], v[116:119], v[44:47]
	s_waitcnt lgkmcnt(0)
	v_mfma_f32_16x16x32_bf16 v[68:71], v[200:203], v[64:67], v[68:71]
	v_mfma_f32_16x16x32_bf16 v[64:67], v[200:203], v[116:119], v[104:107]
	s_branch .LBB0_666

; #define LAS __attribute__((address_space(3)))
; __device__ __forceinline__ void attn_phase(LAS unsigned char* lds, bf16_t* p5, const bf16_t* vt, const float* relb, const float* dalam, const float* subln, float lam_init, int ocol) {
;     ...
;         for (int j = 0; j < njt; ++j) {
;             if (j + 1 < njt) ATT_LOAD(j + 1);
;             if (j * 64 <= qrow0 + 31) {
;                 const LAS unsigned char* kb_ = lds + (j & 1) * KBYTES; const LAS unsigned char* vb_ = lds + 2 * KBYTES + (j & 1) * VBYTES;
;                 bf16x8 kf[4][2];
; #pragma unroll
;                 for (int kb = 0; kb < 4; ++kb)
; #pragma unroll
;                     for (int s = 0; s < 2; ++s) kf[kb][s] = *(const LAS bf16x8*)(kb_ + (16 * kb + lq) * KPITCH + (cc * 64 + s * 32 + 8 * g4) * 2);
;                 __builtin_amdgcn_sched_barrier(0);
;                 f32x4 st[2][4];
; #pragma unroll
;                 for (int kb = 0; kb < 4; ++kb)
; #pragma unroll
;                     for (int rg = 0; rg < 2; ++rg) { f32x4 a = (f32x4){0.f, 0.f, 0.f, 0.f};
; #pragma unroll
;                         for (int s = 0; s < 2; ++s) a = __builtin_amdgcn_mfma_f32_16x16x32_bf16(kf[kb][s], qf[rg][s], a, 0, 0, 0);
;                         st[rg][kb] = a; }
;                 __builtin_amdgcn_sched_barrier(0);
;     ...
;                 u32x2 va[1][2][2];
;                 ATT_VLOAD(va, 0, 1)
;                 __builtin_amdgcn_sched_barrier(0);
;                 const bool far = (j >= 1) && (j * 64 + 63 + 113 <= qrow0);
;                 bf16x8 pk[2][2];
; #pragma unroll
;                 for (int rg = 0; rg < 2; ++rg) {
;                     float rmax = -INFINITY, msafe, alpha;
;                     if (far) {
; #pragma unroll
;                         for (int kb = 0; kb < 4; ++kb)
; #pragma unroll
;                             for (int i = 0; i < 4; ++i) rmax = fmaxf(rmax, st[rg][kb][i]);
;                         rmax = rows4_max(rmax);
;                         const float mnew = fmaxf(mrow[rg], rmax * sc2 + bfar); msafe = mnew;
;                         alpha = __builtin_amdgcn_exp2f(mrow[rg] - msafe); mrow[rg] = mnew;
;                         const float off = bfar - msafe;
; #pragma unroll
;                         for (int kb = 0; kb < 4; ++kb)
; #pragma unroll
;                             for (int i = 0; i < 4; ++i) st[rg][kb][i] = __builtin_amdgcn_exp2f(st[rg][kb][i] * sc2 + off);
.LBB0_666:
	s_lshl_b32 s29, s31, 1
	s_sub_i32 s28, 0, s34
	s_lshl_b32 s19, s30, 7
	s_or_b32 s47, s46, 31
	s_add_i32 s29, s29, 2
	s_cmp_gt_u32 s28, 0xffffffdf
	s_mov_b32 s30, 1
	s_cselect_b32 s48, s29, 0x41
	v_lshl_add_u32 v169, s28, 9, v193
	v_lshl_add_u32 v198, s28, 7, v194
	s_movk_i32 s49, 0xf0
	s_waitcnt vmcnt(3)
	ds_write_b128 v100, v[20:23] offset:17408
	s_waitcnt vmcnt(1)
	ds_write_b128 v101, v[24:27] offset:53248
	ds_write_b128 v102, v[28:31] offset:17408
	s_waitcnt vmcnt(0)
	ds_write_b128 v103, v[32:35] offset:53248
	s_waitcnt lgkmcnt(0)
	s_barrier
	s_movk_i32 s53, 0x4800
	s_mov_b32 s54, 0x9000
	s_mov_b32 s55, 0
.LBB0_667:
	s_add_i32 s50, s30, 1
	s_cmp_lt_u32 s50, s48
	s_cselect_b64 s[28:29], -1, 0
	s_cmp_ge_u32 s50, s48
	s_cbranch_scc1 .LBB0_669
	s_cmp_lg_u32 s55, 0
	s_cbranch_scc1 .LBB0_669
	s_add_i32 s68, s49, 0xffffff90
	v_add_u32_e32 v2, s68, v180
	s_waitcnt vmcnt(0)
	v_lshl_add_u64 v[32:33], s[68:69], 1, v[172:173]
	v_mad_i64_i32 v[20:21], s[34:35], v2, s84, v[170:171]
	v_add_u32_e32 v2, s68, v181
	v_lshl_add_u64 v[24:25], v[32:33], 0, v[150:151]
	v_mad_i64_i32 v[28:29], s[34:35], v2, s84, v[170:171]
	v_lshl_add_u64 v[32:33], v[32:33], 0, v[154:155]
	global_load_dwordx4 v[20:23], v[20:21], off
	s_nop 0
	global_load_dwordx4 v[24:27], v[24:25], off
	s_nop 0
	global_load_dwordx4 v[28:31], v[28:29], off
	s_nop 0
	global_load_dwordx4 v[32:35], v[32:33], off
.LBB0_669:
	s_add_i32 s31, s49, 0xffffff50
	s_cmp_gt_i32 s31, s47
	s_cbranch_scc1 .LBB0_713
	s_and_b32 s30, s30, 1
	s_mul_i32 s31, s30, 0x4400
	v_add3_u32 v2, v175, s31, v186
	ds_read_b128 v[100:103], v2
	ds_read_b128 v[104:107], v2 offset:64
	ds_read_b128 v[108:111], v2 offset:4352
	ds_read_b128 v[112:115], v2 offset:4416
	ds_read_b128 v[124:127], v2 offset:8704
	ds_read_b128 v[200:203], v2 offset:8768
	ds_read_b128 v[204:207], v2 offset:13056
	ds_read_b128 v[224:227], v2 offset:13120
	s_mov_b32 s30, s53
	s_waitcnt lgkmcnt(7)
	v_mfma_f32_16x16x32_bf16 v[116:119], v[100:103], v[4:7], 0
	s_add_i32 s51, s30, 0
	v_mfma_f32_16x16x32_bf16 v[100:103], v[100:103], v[12:15], 0
	s_waitcnt lgkmcnt(6)
	v_mfma_f32_16x16x32_bf16 v[120:123], v[104:107], v[16:19], v[100:103]
	s_waitcnt lgkmcnt(5)
	v_mfma_f32_16x16x32_bf16 v[100:103], v[108:111], v[4:7], 0
	s_waitcnt lgkmcnt(4)
	v_mfma_f32_16x16x32_bf16 v[132:135], v[112:115], v[8:11], v[100:103]
	v_mfma_f32_16x16x32_bf16 v[100:103], v[108:111], v[12:15], 0
	v_mfma_f32_16x16x32_bf16 v[136:139], v[104:107], v[8:11], v[116:119]
	v_mfma_f32_16x16x32_bf16 v[116:119], v[112:115], v[16:19], v[100:103]
	s_waitcnt lgkmcnt(3)
	v_mfma_f32_16x16x32_bf16 v[100:103], v[124:127], v[4:7], 0
	s_waitcnt lgkmcnt(2)
	v_mfma_f32_16x16x32_bf16 v[128:131], v[200:203], v[8:11], v[100:103]
	v_mfma_f32_16x16x32_bf16 v[100:103], v[124:127], v[12:15], 0
	v_mfma_f32_16x16x32_bf16 v[112:115], v[200:203], v[16:19], v[100:103]
	s_waitcnt lgkmcnt(1)
	v_mfma_f32_16x16x32_bf16 v[100:103], v[204:207], v[4:7], 0
	s_waitcnt lgkmcnt(0)
	v_mfma_f32_16x16x32_bf16 v[124:127], v[224:227], v[8:11], v[100:103]
	v_mfma_f32_16x16x32_bf16 v[100:103], v[204:207], v[12:15], 0
	v_mfma_f32_16x16x32_bf16 v[108:111], v[224:227], v[16:19], v[100:103]
	v_add_u32_e32 v2, s51, v176
	v_add_u32_e32 v200, v2, v140
	v_add_u32_e32 v2, 0x8800, v200
	ds_read2_b64 v[104:107], v2 offset1:4
	s_nop 2
	ds_read2_b64 v[100:103], v2 offset0:8 offset1:12
	s_cmp_le_i32 s49, s46
	s_cselect_b64 s[34:35], -1, 0
	s_cmp_gt_i32 s49, s46
	s_mov_b64 s[30:31], -1
	s_cbranch_scc1 .LBB0_672
	v_max3_f32 v2, v136, s87, v137
	v_max3_f32 v2, v2, v138, v139
	v_max3_f32 v2, v2, v132, v133
	v_max3_f32 v2, v2, v134, v135
	v_max3_f32 v2, v2, v128, v129
	v_max3_f32 v2, v2, v130, v131
	v_max3_f32 v2, v2, v124, v125
	v_max3_f32 v2, v2, v126, v127
	v_mov_b32_e32 v161, v2
	s_nop 1
	v_permlane16_swap_b32_e32 v2, v161
	v_max_f32_e32 v161, v161, v161
	v_max_f32_e32 v2, v2, v2
	v_max_f32_e32 v2, v2, v161
	v_mov_b32_e32 v161, v2
	s_nop 1
	v_permlane32_swap_b32_e32 v2, v161
	v_max_f32_e32 v161, v161, v161
	v_max_f32_e32 v2, v2, v2
	v_max_f32_e32 v2, v2, v161
	v_fmamk_f32 v2, v2, 0x3e38aa3b, v222
	v_max_f32_e32 v161, v0, v0
	v_max_f32_e32 v201, v161, v2
	v_sub_f32_e32 v233, v222, v201
	v_fmamk_f32 v2, v136, 0x3e38aa3b, v233
	v_exp_f32_e32 v202, v2
	v_fmamk_f32 v2, v137, 0x3e38aa3b, v233
	v_exp_f32_e32 v203, v2
	v_fmamk_f32 v2, v138, 0x3e38aa3b, v233
	v_exp_f32_e32 v204, v2
	v_fmamk_f32 v2, v139, 0x3e38aa3b, v233
	v_exp_f32_e32 v206, v2
	v_fmamk_f32 v2, v132, 0x3e38aa3b, v233
	v_exp_f32_e32 v205, v2
	v_fmamk_f32 v2, v133, 0x3e38aa3b, v233
	v_exp_f32_e32 v207, v2
	v_fmamk_f32 v2, v134, 0x3e38aa3b, v233
	v_exp_f32_e32 v224, v2
	v_fmamk_f32 v2, v135, 0x3e38aa3b, v233
	v_exp_f32_e32 v226, v2
	v_fmamk_f32 v2, v128, 0x3e38aa3b, v233
	v_exp_f32_e32 v225, v2
	v_fmamk_f32 v2, v129, 0x3e38aa3b, v233
	v_exp_f32_e32 v227, v2
	v_fmamk_f32 v2, v130, 0x3e38aa3b, v233
	v_exp_f32_e32 v228, v2
	v_fmamk_f32 v2, v131, 0x3e38aa3b, v233
	v_exp_f32_e32 v229, v2
	v_fmamk_f32 v2, v124, 0x3e38aa3b, v233
	v_exp_f32_e32 v230, v2
	v_fmamk_f32 v2, v125, 0x3e38aa3b, v233
	v_exp_f32_e32 v231, v2
	v_fmamk_f32 v2, v126, 0x3e38aa3b, v233
	v_exp_f32_e32 v232, v2
	v_fmac_f32_e32 v233, 0x3e38aa3b, v127
	s_mov_b64 s[30:31], 0

; __device__ __forceinline__ unsigned cvt_pk_bf16(float lo, float hi) { unsigned r; asm volatile("v_cvt_pk_bf16_f32 %0, %1, %2" : "=v"(r) : "v"(lo), "v"(hi)); return r; }
; #define ATT_STORE(buf) do { _Pragma("unroll") for (int i = 0; i < 2; ++i) { const int id = tid + 512 * i; \
;             *(LAS u32x4*)(lds + (buf) * KBYTES + (id >> 4) * KPITCH + (id & 15) * 16) = kreg[i]; \
;             *(LAS u32x4*)(lds + 2 * KBYTES + (buf) * VBYTES + (id >> 3) * VPITCH + (id & 7) * 16) = vreg[i]; } } while (0)
; __device__ __forceinline__ void attn_phase(LAS unsigned char* lds, bf16_t* p5, const bf16_t* vt, const float* relb, const float* dalam, const float* subln, float lam_init, int ocol) {
;     ...
;                     float rs = 0.f;
; #pragma unroll
;                     for (int kb = 0; kb < 4; ++kb) rs += (st[rg][kb][0] + st[rg][kb][1]) + (st[rg][kb][2] + st[rg][kb][3]);
;                     lrow[rg] = lrow[rg] * alpha + rs;
;                     if (__builtin_amdgcn_ballot_w64(alpha != 1.0f) != 0ull) {
; #pragma unroll
;                         for (int k = 0; k < 8; ++k) O[rg][k] *= alpha; }
; #pragma unroll
;                     for (int s = 0; s < 2; ++s) { u32x4 w; w.x = cvt_pk_bf16(st[rg][2 * s][0], st[rg][2 * s][1]); w.y = cvt_pk_bf16(st[rg][2 * s][2], st[rg][2 * s][3]);
;                         w.z = cvt_pk_bf16(st[rg][2 * s + 1][0], st[rg][2 * s + 1][1]); w.w = cvt_pk_bf16(st[rg][2 * s + 1][2], st[rg][2 * s + 1][3]);
;                         pk[rg][s] = __builtin_bit_cast(bf16x8, w); }
;                 }
;                 __builtin_amdgcn_sched_barrier(0);
;                 u32x2 vc[3][2][2];
;                 ATT_VLOAD(vc, 1, 3)
;                 __builtin_amdgcn_sched_barrier(0);
;                 ATT_PV(va, 0, 1)
;                 __builtin_amdgcn_sched_barrier(0);
;                 u32x2 vd[2][2][2];
;                 ATT_VLOAD(vd, 4, 2)
;                 __builtin_amdgcn_sched_barrier(0);
;                 ATT_PV(vc, 1, 3)
;                 __builtin_amdgcn_sched_barrier(0);
;                 u32x2 ve[2][2][2];
;                 ATT_VLOAD(ve, 6, 2)
;                 __builtin_amdgcn_sched_barrier(0);
;                 ATT_PV(vd, 4, 2)
;                 __builtin_amdgcn_sched_barrier(0);
;                 ATT_PV(ve, 6, 2)
;     ...
;             }
;             if (j + 1 < njt) ATT_STORE((j + 1) & 1);
;             __syncthreads();
.LBB0_712:
	v_add_f32_e32 v108, v134, v136
	v_add_f32_e32 v109, v135, v138
	v_exp_f32_e32 v115, v242
	v_add_f32_e32 v108, v108, v109
	v_add_f32_e32 v109, v137, v234
	v_add_f32_e32 v110, v233, v237
	v_add_f32_e32 v108, 0, v108
	v_add_f32_e32 v109, v109, v110
	v_add_f32_e32 v108, v108, v109
	v_add_f32_e32 v109, v139, v236
	v_add_f32_e32 v110, v235, v238
	v_add_f32_e32 v109, v109, v110
	v_add_f32_e32 v108, v108, v109
	v_add_f32_e32 v109, v239, v240
	v_add_f32_e32 v110, v115, v241
	v_add_f32_e32 v109, v109, v110
	v_add_f32_e32 v161, v109, v108
	v_fmac_f32_e32 v161, v167, v2
	v_add_f32_e32 v2, v202, v203
	v_add_f32_e32 v108, v204, v206
	v_add_f32_e32 v2, v2, v108
	v_add_f32_e32 v108, v205, v207
	v_add_f32_e32 v109, v224, v226
	v_add_f32_e32 v2, 0, v2
	v_add_f32_e32 v108, v108, v109
	v_add_f32_e32 v2, v2, v108
	v_add_f32_e32 v108, v225, v227
	v_add_f32_e32 v109, v228, v229
	v_add_f32_e32 v108, v108, v109
	v_add_f32_e32 v2, v2, v108
	v_add_f32_e32 v108, v230, v231
	v_add_f32_e32 v109, v132, v232
	v_add_f32_e32 v108, v108, v109
	v_add_f32_e32 v2, v108, v2
	v_fmac_f32_e32 v2, v3, v0
	v_cvt_pk_bf16_f32 v108, v134, v136
	v_cvt_pk_bf16_f32 v109, v135, v138
	v_cvt_pk_bf16_f32 v110, v137, v234
	v_cvt_pk_bf16_f32 v111, v233, v237
	v_cvt_pk_bf16_f32 v112, v139, v236
	v_cvt_pk_bf16_f32 v113, v235, v238
	v_cvt_pk_bf16_f32 v114, v239, v240
	v_cvt_pk_bf16_f32 v115, v241, v115
	s_cmp_eq_u32 s52, 0
	s_cbranch_scc1 .Latt_pv
	s_andn2_b64 vcc, exec, s[28:29]
	s_cbranch_vccnz .Latt_ybar
	s_and_b32 s66, s50, 1
	s_mul_i32 s67, s66, 0x4400
	v_add_u32_e32 v243, s67, v165
	v_add_u32_e32 v244, s54, v174
	v_add_u32_e32 v245, v243, v182
	s_waitcnt vmcnt(3)
	ds_write_b128 v245, v[20:23]
	v_add_u32_e32 v245, v244, v183
	v_add_u32_e32 v243, v243, v184
	s_waitcnt vmcnt(2)
	ds_write_b128 v245, v[24:27] offset:34816
	s_waitcnt vmcnt(1)
	ds_write_b128 v243, v[28:31]
	v_add_u32_e32 v243, v244, v185
	s_waitcnt vmcnt(0)
	ds_write_b128 v243, v[32:35] offset:34816
.Latt_ybar:
	s_waitcnt lgkmcnt(0)
	s_barrier
	s_add_i32 s66, s50, 1
	s_cmp_ge_u32 s66, s48
	s_cbranch_scc1 .Latt_pv
	s_mov_b32 s55, 1
	s_add_i32 s68, s49, 0xffffffd0
	v_add_u32_e32 v243, s68, v180
	v_lshl_add_u64 v[32:33], s[68:69], 1, v[172:173]
	v_mad_i64_i32 v[20:21], vcc, v243, s84, v[170:171]
	v_add_u32_e32 v243, s68, v181
	v_lshl_add_u64 v[24:25], v[32:33], 0, v[150:151]
	v_mad_i64_i32 v[28:29], vcc, v243, s84, v[170:171]
	v_lshl_add_u64 v[32:33], v[32:33], 0, v[154:155]
	global_load_dwordx4 v[20:23], v[20:21], off
	s_nop 0
	global_load_dwordx4 v[24:27], v[24:25], off
	s_nop 0
	global_load_dwordx4 v[28:31], v[28:29], off
	s_nop 0
	global_load_dwordx4 v[32:35], v[32:33], off
.Latt_pv:
	v_add_u32_e32 v0, s51, v140
	v_add_u32_e32 v3, v0, v176
	v_add_u32_e32 v120, 0x9000, v3
	v_add_u32_e32 v132, 0x9800, v3
	v_add_u32_e32 v3, 0xa000, v3
	ds_read2_b64 v[116:119], v120 offset0:32 offset1:36
	ds_read2_b64 v[120:123], v120 offset0:40 offset1:44
	ds_read2_b64 v[134:137], v132 offset0:64 offset1:68
	ds_read2_b64 v[202:205], v132 offset0:72 offset1:76
	ds_read2_b64 v[224:227], v3 offset0:96 offset1:100
	ds_read2_b64 v[228:231], v3 offset0:104 offset1:108
	s_waitcnt lgkmcnt(7)
	v_mfma_f32_16x16x32_bf16 v[88:91], v[104:107], v[124:127], v[88:91]
	v_mfma_f32_16x16x32_bf16 v[40:43], v[104:107], v[108:111], v[40:43]
	s_waitcnt lgkmcnt(6)
	v_mfma_f32_16x16x32_bf16 v[88:91], v[100:103], v[128:131], v[88:91]
	v_mfma_f32_16x16x32_bf16 v[40:43], v[100:103], v[112:115], v[40:43]
	v_add_u32_e32 v3, 0xa800, v200
	v_add_u32_e32 v0, v0, v187
	ds_read2_b64 v[100:103], v3 offset0:128 offset1:132
	ds_read2_b64 v[104:107], v3 offset0:136 offset1:140
	v_add_u32_e32 v3, 0xa800, v0
	ds_read2_b64 v[232:235], v3 offset0:128 offset1:132
	ds_read2_b64 v[236:239], v3 offset0:136 offset1:140
	s_waitcnt lgkmcnt(9)
	v_mfma_f32_16x16x32_bf16 v[92:95], v[116:119], v[124:127], v[92:95]
	v_mfma_f32_16x16x32_bf16 v[56:59], v[116:119], v[108:111], v[56:59]
	s_waitcnt lgkmcnt(7)
	v_mfma_f32_16x16x32_bf16 v[80:83], v[134:137], v[124:127], v[80:83]
	v_mfma_f32_16x16x32_bf16 v[48:51], v[134:137], v[108:111], v[48:51]
	s_waitcnt lgkmcnt(5)
	v_mfma_f32_16x16x32_bf16 v[72:75], v[224:227], v[124:127], v[72:75]
	v_mfma_f32_16x16x32_bf16 v[36:39], v[224:227], v[108:111], v[36:39]
	v_mfma_f32_16x16x32_bf16 v[92:95], v[120:123], v[128:131], v[92:95]
	v_mfma_f32_16x16x32_bf16 v[56:59], v[120:123], v[112:115], v[56:59]
	v_mfma_f32_16x16x32_bf16 v[80:83], v[202:205], v[128:131], v[80:83]
	v_mfma_f32_16x16x32_bf16 v[48:51], v[202:205], v[112:115], v[48:51]
	s_waitcnt lgkmcnt(4)
	v_mfma_f32_16x16x32_bf16 v[72:75], v[228:231], v[128:131], v[72:75]
	v_mfma_f32_16x16x32_bf16 v[36:39], v[228:231], v[112:115], v[36:39]
	v_add_u32_e32 v3, 0xb800, v200
	v_add_u32_e32 v0, 0xb800, v0
	ds_read2_b64 v[116:119], v3 offset0:192 offset1:196
	ds_read2_b64 v[120:123], v3 offset0:200 offset1:204
	ds_read2_b64 v[134:137], v0 offset0:192 offset1:196
	ds_read2_b64 v[202:205], v0 offset0:200 offset1:204
	s_waitcnt lgkmcnt(7)
	v_mfma_f32_16x16x32_bf16 v[96:99], v[100:103], v[124:127], v[96:99]
	v_mfma_f32_16x16x32_bf16 v[60:63], v[100:103], v[108:111], v[60:63]
	s_waitcnt lgkmcnt(5)
	v_mfma_f32_16x16x32_bf16 v[84:87], v[232:235], v[124:127], v[84:87]
	v_mfma_f32_16x16x32_bf16 v[52:55], v[232:235], v[108:111], v[52:55]
	v_mfma_f32_16x16x32_bf16 v[96:99], v[104:107], v[128:131], v[96:99]
	v_mfma_f32_16x16x32_bf16 v[60:63], v[104:107], v[112:115], v[60:63]
	s_waitcnt lgkmcnt(4)
	v_mfma_f32_16x16x32_bf16 v[84:87], v[236:239], v[128:131], v[84:87]
	v_mfma_f32_16x16x32_bf16 v[52:55], v[236:239], v[112:115], v[52:55]
	s_waitcnt lgkmcnt(3)
	v_mfma_f32_16x16x32_bf16 v[76:79], v[116:119], v[124:127], v[76:79]
	v_mov_b32_e32 v167, v161
	v_mov_b32_e32 v3, v2
	v_mfma_f32_16x16x32_bf16 v[44:47], v[116:119], v[108:111], v[44:47]
	s_waitcnt lgkmcnt(1)
	v_mfma_f32_16x16x32_bf16 v[68:71], v[134:137], v[124:127], v[68:71]
	v_mfma_f32_16x16x32_bf16 v[64:67], v[134:137], v[108:111], v[64:67]
	v_mfma_f32_16x16x32_bf16 v[76:79], v[120:123], v[128:131], v[76:79]
	v_mfma_f32_16x16x32_bf16 v[44:47], v[120:123], v[112:115], v[44:47]
	s_waitcnt lgkmcnt(0)
	v_mfma_f32_16x16x32_bf16 v[68:71], v[202:205], v[128:131], v[68:71]
	v_mfma_f32_16x16x32_bf16 v[64:67], v[202:205], v[112:115], v[64:67]
	s_cmp_lg_u32 s52, 0
	s_cbranch_scc1 .Latt_yend
	s_andn2_b64 vcc, exec, s[28:29]
	s_cbranch_vccz .LBB0_714
	s_branch .LBB0_715

; #define ATT_LOAD(j) do { _Pragma("unroll") for (int i = 0; i < 2; ++i) { const int id = tid + 512 * i; \
;             kreg[i] = *(const u32x4*)(kbase + (size_t)((j) * 64 + (id >> 4)) * LDP + (id & 15) * 8); \
;             vreg[i] = *(const u32x4*)(vbase + (size_t)(id >> 3) * TP + (j) * 64 + (id & 7) * 8); } } while (0)
; #define ATT_STORE(buf) do { _Pragma("unroll") for (int i = 0; i < 2; ++i) { const int id = tid + 512 * i; \
;             *(LAS u32x4*)(lds + (buf) * KBYTES + (id >> 4) * KPITCH + (id & 15) * 16) = kreg[i]; \
;             *(LAS u32x4*)(lds + 2 * KBYTES + (buf) * VBYTES + (id >> 3) * VPITCH + (id & 7) * 16) = vreg[i]; } } while (0)
; __device__ __forceinline__ void attn_phase(LAS unsigned char* lds, bf16_t* p5, const bf16_t* vt, const float* relb, const float* dalam, const float* subln, float lam_init, int ocol) {
;     ...
;         for (int j = 0; j < njt; ++j) {
;             if (j + 1 < njt) ATT_LOAD(j + 1);
;     ...
;             if (j + 1 < njt) ATT_STORE((j + 1) & 1);
;             __syncthreads();
;         }
.LBB0_714:
	s_and_b32 s28, s50, 1
	s_mul_i32 s29, s28, 0x4400
	v_add_u32_e32 v0, s29, v165
	s_mov_b32 s28, s54
	v_add_u32_e32 v2, s28, v174
	v_add_u32_e32 v100, v0, v182
	s_waitcnt vmcnt(3)
	ds_write_b128 v100, v[20:23]
	v_add_u32_e32 v100, v2, v183
	v_add_u32_e32 v0, v0, v184
	s_waitcnt vmcnt(2)
	ds_write_b128 v100, v[24:27] offset:34816
	s_waitcnt vmcnt(1)
	ds_write_b128 v0, v[28:31]
	v_add_u32_e32 v0, v2, v185
	s_waitcnt vmcnt(0)
	ds_write_b128 v0, v[32:35] offset:34816
.LBB0_715:
	s_add_i32 s49, s49, 64
	v_add_u32_e32 v169, 0xffffff00, v169
	s_mov_b32 s53, s54
	s_add_i32 s54, s54, 0x4800
	s_cmpk_eq_u32 s54, 0xd800
	s_cselect_b32 s54, 0, s54
	s_cmp_lg_u32 s48, s50
	v_subrev_u32_e32 v198, 64, v198
	s_waitcnt lgkmcnt(0)
	s_barrier
	s_cbranch_scc0 .LBB0_751
.Latt_716:
	v_mov_b32_e32 v0, v201
	v_mov_b32_e32 v199, v133
	s_mov_b32 s30, s50
	s_branch .LBB0_667
.Latt_yend:
	s_add_i32 s49, s49, 64
	v_add_u32_e32 v169, 0xffffff00, v169
	s_mov_b32 s53, s54
	s_add_i32 s54, s54, 0x4800
	s_cmpk_eq_u32 s54, 0xd800
	s_cselect_b32 s54, 0, s54
	v_subrev_u32_e32 v198, 64, v198
	s_cmp_lg_u32 s48, s50
	s_cbranch_scc1 .Latt_716
	s_nop 7
	s_nop 7
	s_branch .LBB0_751

; #define LAS __attribute__((address_space(3)))
; __device__ __forceinline__ void attn_phase(LAS unsigned char* lds, bf16_t* p5, const bf16_t* vt, const float* relb, const float* dalam, const float* subln, float lam_init, int ocol) {
;     ...
;         LAS f32x4* xch = (LAS f32x4*)lds + (size_t)rgi * 2 * 8 * 64 + lane;
; #pragma unroll
;         for (int rg = 0; rg < 2; ++rg) { const float l_ = rows4_sum(lrow[rg]); const float f = l_ > 0.f ? (cc ? lam : 1.0f) / l_ : 0.f;
; #pragma unroll
;             for (int k = 0; k < 8; ++k) { O[rg][k] *= f; if (cc) xch[(rg * 8 + k) * 64] = O[rg][k]; } }
.LBB0_751:
	s_barrier
	v_mov_b32_e32 v0, v3
	s_nop 1
	v_permlane16_swap_b32_e32 v3, v0
	v_add_f32_e32 v0, v3, v0
	v_mov_b32_e32 v2, v0
	s_nop 1
	v_permlane32_swap_b32_e32 v0, v2
	v_add_f32_e32 v0, v0, v2
	v_div_scale_f32 v2, s[28:29], v0, v0, v177
	v_rcp_f32_e32 v3, v2
	s_nop 0
	v_fma_f32 v4, -v2, v3, 1.0
	v_fmac_f32_e32 v3, v4, v3
	v_div_scale_f32 v4, vcc, v177, v0, v177
	v_mul_f32_e32 v5, v4, v3
	v_fma_f32 v6, -v2, v5, v4
	v_fmac_f32_e32 v5, v6, v3
	v_fma_f32 v2, -v2, v5, v4
	v_div_fmas_f32 v2, v2, v3, v5
	v_div_fixup_f32 v2, v2, v0, v177
	v_cmp_lt_f32_e32 vcc, 0, v0
	s_nop 1
	v_cndmask_b32_e32 v2, 0, v2, vcc
	v_pk_mul_f32 v[110:111], v[90:91], v[2:3] op_sel_hi:[1,0]
	v_pk_mul_f32 v[108:109], v[88:89], v[2:3] op_sel_hi:[1,0]
	s_and_b64 vcc, exec, s[16:17]
	s_cbranch_vccz .LBB0_753
	ds_write_b128 v197, v[108:111]
